# row-sum cross-lane reductions in the P4/P5/P6 epilogues: v_permlane16/32_swap instead of ds_bpermute round trips (40 of 64 sites)
# speedup vs baseline: 1.0060x; 1.0060x over previous
; __device__ __forceinline__ unsigned cvt_pk_bf16(float lo, float hi) { const f32x2c_t v = {lo, hi}; const bf16x2c_t b = __builtin_convertvector(v, bf16x2c_t); return __builtin_bit_cast(unsigned, b); }
;     __device__ __forceinline__ void operator()(const f32x4 (&acc)[2][2][4][2], const Unit& u, int wr, int wc, int fr, int fq) const {
;     ...
;                 for (int bj = 0; bj < 2; ++bj) { const size_t off = (size_t)(row0 + ai * HALF + m * 16) * DM + col0 + bj * HALF; xv[m][bj][0] = *(const f32x4*)(xbase + off); xv[m][bj][1] = *(const f32x4*)(xbase + off + 4); }
; #pragma unroll
;             for (int m = 0; m < 4; ++m) { const size_t r = (size_t)(row0 + ai * HALF + m * 16); float ss = 0.f;
; #pragma unroll
;                 for (int bj = 0; bj < 2; ++bj) { const size_t off = r * DM + col0 + bj * HALF;
;                     const f32x4 v0 = acc[ai][bj][m][0] * ascale + xv[m][bj][0], v1 = acc[ai][bj][m][1] * ascale + xv[m][bj][1];
;                     if (!WB) { *(f32x4*)(out + off) = v0; *(f32x4*)(out + off + 4) = v1; }
;                     if (WB) { u32x4 w; w.x = cvt_pk_bf16(v0[0], v0[1]); w.y = cvt_pk_bf16(v0[2], v0[3]); w.z = cvt_pk_bf16(v1[0], v1[1]); w.w = cvt_pk_bf16(v1[2], v1[3]); *(u32x4*)(xb + off) = w; }
;                     ss += (v0[0] * v0[0] + v0[1] * v0[1]) + (v0[2] * v0[2] + v0[3] * v0[3]) + (v1[0] * v1[0] + v1[1] * v1[1]) + (v1[2] * v1[2] + v1[3] * v1[3]); }
;                 ss += __shfl_xor(ss, 16); ss += __shfl_xor(ss, 32);
;                 if (fq == 0) ssq[r * 16 + u.pn * 4 + wc] = ss; }
.Lmy_ab_p4:
	v_and_b32_e32 v196, 64, v204
	v_add_u32_e32 v196, 64, v196
	v_xor_b32_e32 v205, 16, v204
	v_cmp_lt_i32_e32 vcc, v205, v196
	s_nop 1
	v_cndmask_b32_e32 v205, v204, v205, vcc
	v_lshlrev_b32_e32 v205, 2, v205
	v_xor_b32_e32 v206, 32, v204
	v_cmp_lt_i32_e32 vcc, v206, v196
	s_nop 1
	v_cndmask_b32_e32 v206, v204, v206, vcc
	v_lshlrev_b32_e32 v206, 2, v206
	v_cmp_gt_u32_e32 vcc, 16, v178
	s_waitcnt vmcnt(20)
	v_pk_fma_f32 v[116:117], v[116:117], s[40:41], v[128:129] op_sel_hi:[1,0,1]
	v_pk_fma_f32 v[118:119], v[118:119], s[40:41], v[130:131] op_sel_hi:[1,0,1]
	v_pk_fma_f32 v[112:113], v[112:113], s[40:41], v[132:133] op_sel_hi:[1,0,1]
	v_pk_fma_f32 v[114:115], v[114:115], s[40:41], v[134:135] op_sel_hi:[1,0,1]
	v_pk_fma_f32 v[124:125], v[124:125], s[40:41], v[136:137] op_sel_hi:[1,0,1]
	v_pk_fma_f32 v[126:127], v[126:127], s[40:41], v[138:139] op_sel_hi:[1,0,1]
	v_pk_fma_f32 v[120:121], v[120:121], s[40:41], v[140:141] op_sel_hi:[1,0,1]
	v_pk_fma_f32 v[122:123], v[122:123], s[40:41], v[142:143] op_sel_hi:[1,0,1]
	v_mul_f32_e32 v128, v117, v117
	v_mul_f32_e32 v129, v119, v119
	v_mul_f32_e32 v130, v113, v113
	v_mul_f32_e32 v131, v115, v115
	v_mul_f32_e32 v132, v125, v125
	v_mul_f32_e32 v133, v127, v127
	v_mul_f32_e32 v134, v121, v121
	v_mul_f32_e32 v135, v123, v123
	v_fmac_f32_e32 v128, v116, v116
	v_fmac_f32_e32 v129, v118, v118
	v_fmac_f32_e32 v130, v112, v112
	v_fmac_f32_e32 v131, v114, v114
	v_fmac_f32_e32 v132, v124, v124
	v_fmac_f32_e32 v133, v126, v126
	v_fmac_f32_e32 v134, v120, v120
	v_fmac_f32_e32 v135, v122, v122
	v_cvt_pk_bf16_f32 v136, v116, v117
	v_cvt_pk_bf16_f32 v137, v118, v119
	v_cvt_pk_bf16_f32 v138, v112, v113
	v_cvt_pk_bf16_f32 v139, v114, v115
	v_cvt_pk_bf16_f32 v140, v124, v125
	v_cvt_pk_bf16_f32 v141, v126, v127
	v_cvt_pk_bf16_f32 v142, v120, v121
	v_cvt_pk_bf16_f32 v143, v122, v123
	global_store_dwordx4 v[224:225], v[136:139], off
	global_store_dwordx4 v[224:225], v[140:143], off offset:256
	v_add_f32_e32 v128, v128, v129
	v_add_f32_e32 v130, v130, v131
	v_add_f32_e32 v132, v132, v133
	v_add_f32_e32 v134, v134, v135
	v_add_f32_e32 v128, v128, v130
	v_add_f32_e32 v132, v132, v134
	v_add_f32_e32 v128, v128, v132
	v_mov_b32_e32 v129, v128
	s_nop 1
	v_permlane16_swap_b32_e32 v128, v129
	s_nop 0
	v_add_f32_e32 v128, v128, v129
	v_mov_b32_e32 v129, v128
	s_nop 1
	v_permlane32_swap_b32_e32 v128, v129
	s_nop 0
	v_add_f32_e32 v128, v128, v129
	s_and_saveexec_b64 s[50:51], vcc
	global_store_dword v[226:227], v128, off
	s_or_b64 exec, exec, s[50:51]
	v_lshl_add_u64 v[224:225], v[224:225], 0, s[82:83]
	v_lshl_add_u64 v[226:227], v[226:227], 0, s[86:87]
	global_load_dwordx4 v[128:131], v[252:253], off
	global_load_dwordx4 v[132:135], v[252:253], off offset:16
	global_load_dwordx4 v[136:139], v[252:253], off offset:512
	global_load_dwordx4 v[140:143], v[252:253], off offset:528
	v_lshl_add_u64 v[252:253], v[252:253], 0, s[78:79]
	s_waitcnt vmcnt(23)
	v_pk_fma_f32 v[108:109], v[108:109], s[40:41], v[144:145] op_sel_hi:[1,0,1]
	v_pk_fma_f32 v[110:111], v[110:111], s[40:41], v[146:147] op_sel_hi:[1,0,1]
	v_pk_fma_f32 v[100:101], v[100:101], s[40:41], v[148:149] op_sel_hi:[1,0,1]
	v_pk_fma_f32 v[102:103], v[102:103], s[40:41], v[150:151] op_sel_hi:[1,0,1]
	v_pk_fma_f32 v[104:105], v[104:105], s[40:41], v[152:153] op_sel_hi:[1,0,1]
	v_pk_fma_f32 v[106:107], v[106:107], s[40:41], v[154:155] op_sel_hi:[1,0,1]
	v_pk_fma_f32 v[96:97], v[96:97], s[40:41], v[156:157] op_sel_hi:[1,0,1]
	v_pk_fma_f32 v[98:99], v[98:99], s[40:41], v[158:159] op_sel_hi:[1,0,1]
	v_mul_f32_e32 v144, v109, v109
	v_mul_f32_e32 v145, v111, v111
	v_mul_f32_e32 v146, v101, v101
	v_mul_f32_e32 v147, v103, v103
	v_mul_f32_e32 v148, v105, v105
	v_mul_f32_e32 v149, v107, v107
	v_mul_f32_e32 v150, v97, v97
	v_mul_f32_e32 v151, v99, v99
	v_fmac_f32_e32 v144, v108, v108
	v_fmac_f32_e32 v145, v110, v110
	v_fmac_f32_e32 v146, v100, v100
	v_fmac_f32_e32 v147, v102, v102
	v_fmac_f32_e32 v148, v104, v104
	v_fmac_f32_e32 v149, v106, v106
	v_fmac_f32_e32 v150, v96, v96
	v_fmac_f32_e32 v151, v98, v98
	v_cvt_pk_bf16_f32 v152, v108, v109
	v_cvt_pk_bf16_f32 v153, v110, v111
	v_cvt_pk_bf16_f32 v154, v100, v101
	v_cvt_pk_bf16_f32 v155, v102, v103
	v_cvt_pk_bf16_f32 v156, v104, v105
	v_cvt_pk_bf16_f32 v157, v106, v107
	v_cvt_pk_bf16_f32 v158, v96, v97
	v_cvt_pk_bf16_f32 v159, v98, v99
	global_store_dwordx4 v[224:225], v[152:155], off
	global_store_dwordx4 v[224:225], v[156:159], off offset:256
	v_add_f32_e32 v144, v144, v145
	v_add_f32_e32 v146, v146, v147
	v_add_f32_e32 v148, v148, v149
	v_add_f32_e32 v150, v150, v151
	v_add_f32_e32 v144, v144, v146
	v_add_f32_e32 v148, v148, v150
	v_add_f32_e32 v144, v144, v148
	v_mov_b32_e32 v145, v144
	s_nop 1
	v_permlane16_swap_b32_e32 v144, v145
	s_nop 0
	v_add_f32_e32 v144, v144, v145
	v_mov_b32_e32 v145, v144
	s_nop 1
	v_permlane32_swap_b32_e32 v144, v145
	s_nop 0
	v_add_f32_e32 v144, v144, v145
	s_and_saveexec_b64 s[50:51], vcc
	global_store_dword v[226:227], v144, off
	s_or_b64 exec, exec, s[50:51]
	v_lshl_add_u64 v[224:225], v[224:225], 0, s[82:83]
	v_lshl_add_u64 v[226:227], v[226:227], 0, s[86:87]
	global_load_dwordx4 v[144:147], v[252:253], off
	global_load_dwordx4 v[148:151], v[252:253], off offset:16
	global_load_dwordx4 v[152:155], v[252:253], off offset:512
	global_load_dwordx4 v[156:159], v[252:253], off offset:528
	s_waitcnt vmcnt(26)
; __device__ __forceinline__ unsigned cvt_pk_bf16(float lo, float hi) { const f32x2c_t v = {lo, hi}; const bf16x2c_t b = __builtin_convertvector(v, bf16x2c_t); return __builtin_bit_cast(unsigned, b); }
;     __device__ __forceinline__ void operator()(const f32x4 (&acc)[2][2][4][2], const Unit& u, int wr, int wc, int fr, int fq) const {
;     ...
;                 for (int bj = 0; bj < 2; ++bj) { const size_t off = (size_t)(row0 + ai * HALF + m * 16) * DM + col0 + bj * HALF; xv[m][bj][0] = *(const f32x4*)(xbase + off); xv[m][bj][1] = *(const f32x4*)(xbase + off + 4); }
; #pragma unroll
;             for (int m = 0; m < 4; ++m) { const size_t r = (size_t)(row0 + ai * HALF + m * 16); float ss = 0.f;
; #pragma unroll
;                 for (int bj = 0; bj < 2; ++bj) { const size_t off = r * DM + col0 + bj * HALF;
;                     const f32x4 v0 = acc[ai][bj][m][0] * ascale + xv[m][bj][0], v1 = acc[ai][bj][m][1] * ascale + xv[m][bj][1];
;                     if (!WB) { *(f32x4*)(out + off) = v0; *(f32x4*)(out + off + 4) = v1; }
;                     if (WB) { u32x4 w; w.x = cvt_pk_bf16(v0[0], v0[1]); w.y = cvt_pk_bf16(v0[2], v0[3]); w.z = cvt_pk_bf16(v1[0], v1[1]); w.w = cvt_pk_bf16(v1[2], v1[3]); *(u32x4*)(xb + off) = w; }
;                     ss += (v0[0] * v0[0] + v0[1] * v0[1]) + (v0[2] * v0[2] + v0[3] * v0[3]) + (v1[0] * v1[0] + v1[1] * v1[1]) + (v1[2] * v1[2] + v1[3] * v1[3]); }
;                 ss += __shfl_xor(ss, 16); ss += __shfl_xor(ss, 32);
;                 if (fq == 0) ssq[r * 16 + u.pn * 4 + wc] = ss; }
	v_pk_fma_f32 v[92:93], v[92:93], s[40:41], v[160:161] op_sel_hi:[1,0,1]
	v_pk_fma_f32 v[94:95], v[94:95], s[40:41], v[162:163] op_sel_hi:[1,0,1]
	v_pk_fma_f32 v[84:85], v[84:85], s[40:41], v[164:165] op_sel_hi:[1,0,1]
	v_pk_fma_f32 v[86:87], v[86:87], s[40:41], v[166:167] op_sel_hi:[1,0,1]
	v_pk_fma_f32 v[88:89], v[88:89], s[40:41], v[168:169] op_sel_hi:[1,0,1]
	v_pk_fma_f32 v[90:91], v[90:91], s[40:41], v[170:171] op_sel_hi:[1,0,1]
	v_pk_fma_f32 v[80:81], v[80:81], s[40:41], v[172:173] op_sel_hi:[1,0,1]
	v_pk_fma_f32 v[82:83], v[82:83], s[40:41], v[174:175] op_sel_hi:[1,0,1]
	v_mul_f32_e32 v160, v93, v93
	v_mul_f32_e32 v161, v95, v95
	v_mul_f32_e32 v162, v85, v85
	v_mul_f32_e32 v163, v87, v87
	v_mul_f32_e32 v164, v89, v89
	v_mul_f32_e32 v165, v91, v91
	v_mul_f32_e32 v166, v81, v81
	v_mul_f32_e32 v167, v83, v83
	v_fmac_f32_e32 v160, v92, v92
	v_fmac_f32_e32 v161, v94, v94
	v_fmac_f32_e32 v162, v84, v84
	v_fmac_f32_e32 v163, v86, v86
	v_fmac_f32_e32 v164, v88, v88
	v_fmac_f32_e32 v165, v90, v90
	v_fmac_f32_e32 v166, v80, v80
	v_fmac_f32_e32 v167, v82, v82
	v_cvt_pk_bf16_f32 v168, v92, v93
	v_cvt_pk_bf16_f32 v169, v94, v95
	v_cvt_pk_bf16_f32 v170, v84, v85
	v_cvt_pk_bf16_f32 v171, v86, v87
	v_cvt_pk_bf16_f32 v172, v88, v89
	v_cvt_pk_bf16_f32 v173, v90, v91
	v_cvt_pk_bf16_f32 v174, v80, v81
	v_cvt_pk_bf16_f32 v175, v82, v83
	global_store_dwordx4 v[224:225], v[168:171], off
	global_store_dwordx4 v[224:225], v[172:175], off offset:256
	v_add_f32_e32 v160, v160, v161
	v_add_f32_e32 v162, v162, v163
	v_add_f32_e32 v164, v164, v165
	v_add_f32_e32 v166, v166, v167
	v_add_f32_e32 v160, v160, v162
	v_add_f32_e32 v164, v164, v166
	v_add_f32_e32 v160, v160, v164
	v_mov_b32_e32 v161, v160
	s_nop 1
	v_permlane16_swap_b32_e32 v160, v161
	s_nop 0
	v_add_f32_e32 v160, v160, v161
	v_mov_b32_e32 v161, v160
	s_nop 1
	v_permlane32_swap_b32_e32 v160, v161
	s_nop 0
	v_add_f32_e32 v160, v160, v161
	s_and_saveexec_b64 s[50:51], vcc
	global_store_dword v[226:227], v160, off
	s_or_b64 exec, exec, s[50:51]
	v_lshl_add_u64 v[224:225], v[224:225], 0, s[82:83]
	v_lshl_add_u64 v[226:227], v[226:227], 0, s[86:87]
	s_waitcnt vmcnt(25)
	v_pk_fma_f32 v[76:77], v[76:77], s[40:41], v[180:181] op_sel_hi:[1,0,1]
	v_pk_fma_f32 v[78:79], v[78:79], s[40:41], v[182:183] op_sel_hi:[1,0,1]
	v_pk_fma_f32 v[68:69], v[68:69], s[40:41], v[184:185] op_sel_hi:[1,0,1]
	v_pk_fma_f32 v[70:71], v[70:71], s[40:41], v[186:187] op_sel_hi:[1,0,1]
	v_pk_fma_f32 v[72:73], v[72:73], s[40:41], v[188:189] op_sel_hi:[1,0,1]
	v_pk_fma_f32 v[74:75], v[74:75], s[40:41], v[190:191] op_sel_hi:[1,0,1]
	v_pk_fma_f32 v[64:65], v[64:65], s[40:41], v[192:193] op_sel_hi:[1,0,1]
	v_pk_fma_f32 v[66:67], v[66:67], s[40:41], v[194:195] op_sel_hi:[1,0,1]
	v_mul_f32_e32 v180, v77, v77
	v_mul_f32_e32 v181, v79, v79
	v_mul_f32_e32 v182, v69, v69
	v_mul_f32_e32 v183, v71, v71
	v_mul_f32_e32 v184, v73, v73
	v_mul_f32_e32 v185, v75, v75
	v_mul_f32_e32 v186, v65, v65
	v_mul_f32_e32 v187, v67, v67
	v_fmac_f32_e32 v180, v76, v76
	v_fmac_f32_e32 v181, v78, v78
	v_fmac_f32_e32 v182, v68, v68
	v_fmac_f32_e32 v183, v70, v70
	v_fmac_f32_e32 v184, v72, v72
	v_fmac_f32_e32 v185, v74, v74
	v_fmac_f32_e32 v186, v64, v64
	v_fmac_f32_e32 v187, v66, v66
	v_cvt_pk_bf16_f32 v188, v76, v77
	v_cvt_pk_bf16_f32 v189, v78, v79
	v_cvt_pk_bf16_f32 v190, v68, v69
	v_cvt_pk_bf16_f32 v191, v70, v71
	v_cvt_pk_bf16_f32 v192, v72, v73
	v_cvt_pk_bf16_f32 v193, v74, v75
	v_cvt_pk_bf16_f32 v194, v64, v65
	v_cvt_pk_bf16_f32 v195, v66, v67
	global_store_dwordx4 v[224:225], v[188:191], off
	global_store_dwordx4 v[224:225], v[192:195], off offset:256
	v_add_f32_e32 v180, v180, v181
	v_add_f32_e32 v182, v182, v183
	v_add_f32_e32 v184, v184, v185
	v_add_f32_e32 v186, v186, v187
	v_add_f32_e32 v180, v180, v182
	v_add_f32_e32 v184, v184, v186
	v_add_f32_e32 v180, v180, v184
	v_mov_b32_e32 v181, v180
	s_nop 1
	v_permlane16_swap_b32_e32 v180, v181
	s_nop 0
	v_add_f32_e32 v180, v180, v181
	v_mov_b32_e32 v181, v180
	s_nop 1
	v_permlane32_swap_b32_e32 v180, v181
	s_nop 0
	v_add_f32_e32 v180, v180, v181
	s_and_saveexec_b64 s[50:51], vcc
	global_store_dword v[226:227], v180, off
	s_or_b64 exec, exec, s[50:51]
	v_lshl_add_u64 v[224:225], v[224:225], 0, s[84:85]
	v_lshl_add_u64 v[226:227], v[226:227], 0, s[88:89]
	s_waitcnt vmcnt(24)
	v_pk_fma_f32 v[52:53], v[52:53], s[40:41], v[208:209] op_sel_hi:[1,0,1]
	v_pk_fma_f32 v[54:55], v[54:55], s[40:41], v[210:211] op_sel_hi:[1,0,1]
	v_pk_fma_f32 v[48:49], v[48:49], s[40:41], v[212:213] op_sel_hi:[1,0,1]
	v_pk_fma_f32 v[50:51], v[50:51], s[40:41], v[214:215] op_sel_hi:[1,0,1]
	v_pk_fma_f32 v[60:61], v[60:61], s[40:41], v[216:217] op_sel_hi:[1,0,1]
	v_pk_fma_f32 v[62:63], v[62:63], s[40:41], v[218:219] op_sel_hi:[1,0,1]
	v_pk_fma_f32 v[56:57], v[56:57], s[40:41], v[220:221] op_sel_hi:[1,0,1]
	v_pk_fma_f32 v[58:59], v[58:59], s[40:41], v[222:223] op_sel_hi:[1,0,1]
	v_mul_f32_e32 v208, v53, v53
	v_mul_f32_e32 v209, v55, v55
	v_mul_f32_e32 v210, v49, v49
	v_mul_f32_e32 v211, v51, v51
	v_mul_f32_e32 v212, v61, v61
	v_mul_f32_e32 v213, v63, v63
	v_mul_f32_e32 v214, v57, v57
	v_mul_f32_e32 v215, v59, v59
	v_fmac_f32_e32 v208, v52, v52
	v_fmac_f32_e32 v209, v54, v54
	v_fmac_f32_e32 v210, v48, v48
	v_fmac_f32_e32 v211, v50, v50
	v_fmac_f32_e32 v212, v60, v60
	v_fmac_f32_e32 v213, v62, v62
	v_fmac_f32_e32 v214, v56, v56
	v_fmac_f32_e32 v215, v58, v58
	v_cvt_pk_bf16_f32 v216, v52, v53
	v_cvt_pk_bf16_f32 v217, v54, v55
	v_cvt_pk_bf16_f32 v218, v48, v49
	v_cvt_pk_bf16_f32 v219, v50, v51
	v_cvt_pk_bf16_f32 v220, v60, v61
	v_cvt_pk_bf16_f32 v221, v62, v63
	v_cvt_pk_bf16_f32 v222, v56, v57
	v_cvt_pk_bf16_f32 v223, v58, v59
	global_store_dwordx4 v[224:225], v[216:219], off
	global_store_dwordx4 v[224:225], v[220:223], off offset:256
	v_add_f32_e32 v208, v208, v209
	v_add_f32_e32 v210, v210, v211
	v_add_f32_e32 v212, v212, v213
	v_add_f32_e32 v214, v214, v215
	v_add_f32_e32 v208, v208, v210
	v_add_f32_e32 v212, v212, v214
	v_add_f32_e32 v208, v208, v212
	v_mov_b32_e32 v209, v208
	s_nop 1
	v_permlane16_swap_b32_e32 v208, v209
	s_nop 0
	v_add_f32_e32 v208, v208, v209
	v_mov_b32_e32 v209, v208
	s_nop 1
	v_permlane32_swap_b32_e32 v208, v209
	s_nop 0
	v_add_f32_e32 v208, v208, v209
	s_and_saveexec_b64 s[50:51], vcc
	global_store_dword v[226:227], v208, off
	s_or_b64 exec, exec, s[50:51]
	v_lshl_add_u64 v[224:225], v[224:225], 0, s[82:83]
	v_lshl_add_u64 v[226:227], v[226:227], 0, s[86:87]
	s_waitcnt vmcnt(23)
; __device__ __forceinline__ unsigned cvt_pk_bf16(float lo, float hi) { const f32x2c_t v = {lo, hi}; const bf16x2c_t b = __builtin_convertvector(v, bf16x2c_t); return __builtin_bit_cast(unsigned, b); }
;     __device__ __forceinline__ void operator()(const f32x4 (&acc)[2][2][4][2], const Unit& u, int wr, int wc, int fr, int fq) const {
;     ...
;                 for (int bj = 0; bj < 2; ++bj) { const size_t off = (size_t)(row0 + ai * HALF + m * 16) * DM + col0 + bj * HALF; xv[m][bj][0] = *(const f32x4*)(xbase + off); xv[m][bj][1] = *(const f32x4*)(xbase + off + 4); }
; #pragma unroll
;             for (int m = 0; m < 4; ++m) { const size_t r = (size_t)(row0 + ai * HALF + m * 16); float ss = 0.f;
; #pragma unroll
;                 for (int bj = 0; bj < 2; ++bj) { const size_t off = r * DM + col0 + bj * HALF;
;                     const f32x4 v0 = acc[ai][bj][m][0] * ascale + xv[m][bj][0], v1 = acc[ai][bj][m][1] * ascale + xv[m][bj][1];
;                     if (!WB) { *(f32x4*)(out + off) = v0; *(f32x4*)(out + off + 4) = v1; }
;                     if (WB) { u32x4 w; w.x = cvt_pk_bf16(v0[0], v0[1]); w.y = cvt_pk_bf16(v0[2], v0[3]); w.z = cvt_pk_bf16(v1[0], v1[1]); w.w = cvt_pk_bf16(v1[2], v1[3]); *(u32x4*)(xb + off) = w; }
;                     ss += (v0[0] * v0[0] + v0[1] * v0[1]) + (v0[2] * v0[2] + v0[3] * v0[3]) + (v1[0] * v1[0] + v1[1] * v1[1]) + (v1[2] * v1[2] + v1[3] * v1[3]); }
;                 ss += __shfl_xor(ss, 16); ss += __shfl_xor(ss, 32);
;                 if (fq == 0) ssq[r * 16 + u.pn * 4 + wc] = ss; }
	v_pk_fma_f32 v[44:45], v[44:45], s[40:41], v[236:237] op_sel_hi:[1,0,1]
	v_pk_fma_f32 v[46:47], v[46:47], s[40:41], v[238:239] op_sel_hi:[1,0,1]
	v_pk_fma_f32 v[36:37], v[36:37], s[40:41], v[240:241] op_sel_hi:[1,0,1]
	v_pk_fma_f32 v[38:39], v[38:39], s[40:41], v[242:243] op_sel_hi:[1,0,1]
	v_pk_fma_f32 v[40:41], v[40:41], s[40:41], v[244:245] op_sel_hi:[1,0,1]
	v_pk_fma_f32 v[42:43], v[42:43], s[40:41], v[246:247] op_sel_hi:[1,0,1]
	v_pk_fma_f32 v[32:33], v[32:33], s[40:41], v[248:249] op_sel_hi:[1,0,1]
	v_pk_fma_f32 v[34:35], v[34:35], s[40:41], v[250:251] op_sel_hi:[1,0,1]
	v_mul_f32_e32 v236, v45, v45
	v_mul_f32_e32 v237, v47, v47
	v_mul_f32_e32 v238, v37, v37
	v_mul_f32_e32 v239, v39, v39
	v_mul_f32_e32 v240, v41, v41
	v_mul_f32_e32 v241, v43, v43
	v_mul_f32_e32 v242, v33, v33
	v_mul_f32_e32 v243, v35, v35
	v_fmac_f32_e32 v236, v44, v44
	v_fmac_f32_e32 v237, v46, v46
	v_fmac_f32_e32 v238, v36, v36
	v_fmac_f32_e32 v239, v38, v38
	v_fmac_f32_e32 v240, v40, v40
	v_fmac_f32_e32 v241, v42, v42
	v_fmac_f32_e32 v242, v32, v32
	v_fmac_f32_e32 v243, v34, v34
	v_cvt_pk_bf16_f32 v244, v44, v45
	v_cvt_pk_bf16_f32 v245, v46, v47
	v_cvt_pk_bf16_f32 v246, v36, v37
	v_cvt_pk_bf16_f32 v247, v38, v39
	v_cvt_pk_bf16_f32 v248, v40, v41
	v_cvt_pk_bf16_f32 v249, v42, v43
	v_cvt_pk_bf16_f32 v250, v32, v33
	v_cvt_pk_bf16_f32 v251, v34, v35
	global_store_dwordx4 v[224:225], v[244:247], off
	global_store_dwordx4 v[224:225], v[248:251], off offset:256
	v_add_f32_e32 v236, v236, v237
	v_add_f32_e32 v238, v238, v239
	v_add_f32_e32 v240, v240, v241
	v_add_f32_e32 v242, v242, v243
	v_add_f32_e32 v236, v236, v238
	v_add_f32_e32 v240, v240, v242
	v_add_f32_e32 v236, v236, v240
	v_mov_b32_e32 v237, v236
	s_nop 1
	v_permlane16_swap_b32_e32 v236, v237
	s_nop 0
	v_add_f32_e32 v236, v236, v237
	v_mov_b32_e32 v237, v236
	s_nop 1
	v_permlane32_swap_b32_e32 v236, v237
	s_nop 0
	v_add_f32_e32 v236, v236, v237
	s_and_saveexec_b64 s[50:51], vcc
	global_store_dword v[226:227], v236, off
	s_or_b64 exec, exec, s[50:51]
	v_lshl_add_u64 v[224:225], v[224:225], 0, s[82:83]
	v_lshl_add_u64 v[226:227], v[226:227], 0, s[86:87]
	s_waitcnt vmcnt(19)
	v_pk_fma_f32 v[28:29], v[28:29], s[40:41], v[128:129] op_sel_hi:[1,0,1]
	v_pk_fma_f32 v[30:31], v[30:31], s[40:41], v[130:131] op_sel_hi:[1,0,1]
	v_pk_fma_f32 v[20:21], v[20:21], s[40:41], v[132:133] op_sel_hi:[1,0,1]
	v_pk_fma_f32 v[22:23], v[22:23], s[40:41], v[134:135] op_sel_hi:[1,0,1]
	v_pk_fma_f32 v[24:25], v[24:25], s[40:41], v[136:137] op_sel_hi:[1,0,1]
	v_pk_fma_f32 v[26:27], v[26:27], s[40:41], v[138:139] op_sel_hi:[1,0,1]
	v_pk_fma_f32 v[16:17], v[16:17], s[40:41], v[140:141] op_sel_hi:[1,0,1]
	v_pk_fma_f32 v[18:19], v[18:19], s[40:41], v[142:143] op_sel_hi:[1,0,1]
	v_mul_f32_e32 v128, v29, v29
	v_mul_f32_e32 v129, v31, v31
	v_mul_f32_e32 v130, v21, v21
	v_mul_f32_e32 v131, v23, v23
	v_mul_f32_e32 v132, v25, v25
	v_mul_f32_e32 v133, v27, v27
	v_mul_f32_e32 v134, v17, v17
	v_mul_f32_e32 v135, v19, v19
	v_fmac_f32_e32 v128, v28, v28
	v_fmac_f32_e32 v129, v30, v30
	v_fmac_f32_e32 v130, v20, v20
	v_fmac_f32_e32 v131, v22, v22
	v_fmac_f32_e32 v132, v24, v24
	v_fmac_f32_e32 v133, v26, v26
	v_fmac_f32_e32 v134, v16, v16
	v_fmac_f32_e32 v135, v18, v18
	v_cvt_pk_bf16_f32 v136, v28, v29
	v_cvt_pk_bf16_f32 v137, v30, v31
	v_cvt_pk_bf16_f32 v138, v20, v21
	v_cvt_pk_bf16_f32 v139, v22, v23
	v_cvt_pk_bf16_f32 v140, v24, v25
	v_cvt_pk_bf16_f32 v141, v26, v27
	v_cvt_pk_bf16_f32 v142, v16, v17
	v_cvt_pk_bf16_f32 v143, v18, v19
	global_store_dwordx4 v[224:225], v[136:139], off
	global_store_dwordx4 v[224:225], v[140:143], off offset:256
	v_add_f32_e32 v128, v128, v129
	v_add_f32_e32 v130, v130, v131
	v_add_f32_e32 v132, v132, v133
	v_add_f32_e32 v134, v134, v135
	v_add_f32_e32 v128, v128, v130
	v_add_f32_e32 v132, v132, v134
	v_add_f32_e32 v128, v128, v132
	v_mov_b32_e32 v129, v128
	s_nop 1
	v_permlane16_swap_b32_e32 v128, v129
	s_nop 0
	v_add_f32_e32 v128, v128, v129
	v_mov_b32_e32 v129, v128
	s_nop 1
	v_permlane32_swap_b32_e32 v128, v129
	s_nop 0
	v_add_f32_e32 v128, v128, v129
	s_and_saveexec_b64 s[50:51], vcc
	global_store_dword v[226:227], v128, off
	s_or_b64 exec, exec, s[50:51]
	v_lshl_add_u64 v[224:225], v[224:225], 0, s[82:83]
	v_lshl_add_u64 v[226:227], v[226:227], 0, s[86:87]
	s_waitcnt vmcnt(15)
	v_pk_fma_f32 v[12:13], v[12:13], s[40:41], v[144:145] op_sel_hi:[1,0,1]
	v_pk_fma_f32 v[14:15], v[14:15], s[40:41], v[146:147] op_sel_hi:[1,0,1]
	v_pk_fma_f32 v[4:5], v[4:5], s[40:41], v[148:149] op_sel_hi:[1,0,1]
	v_pk_fma_f32 v[6:7], v[6:7], s[40:41], v[150:151] op_sel_hi:[1,0,1]
	v_pk_fma_f32 v[8:9], v[8:9], s[40:41], v[152:153] op_sel_hi:[1,0,1]
	v_pk_fma_f32 v[10:11], v[10:11], s[40:41], v[154:155] op_sel_hi:[1,0,1]
	v_pk_fma_f32 v[0:1], v[0:1], s[40:41], v[156:157] op_sel_hi:[1,0,1]
	v_pk_fma_f32 v[2:3], v[2:3], s[40:41], v[158:159] op_sel_hi:[1,0,1]
	v_mul_f32_e32 v144, v13, v13
	v_mul_f32_e32 v145, v15, v15
	v_mul_f32_e32 v146, v5, v5
	v_mul_f32_e32 v147, v7, v7
	v_mul_f32_e32 v148, v9, v9
	v_mul_f32_e32 v149, v11, v11
	v_mul_f32_e32 v150, v1, v1
	v_mul_f32_e32 v151, v3, v3
	v_fmac_f32_e32 v144, v12, v12
	v_fmac_f32_e32 v145, v14, v14
	v_fmac_f32_e32 v146, v4, v4
	v_fmac_f32_e32 v147, v6, v6
	v_fmac_f32_e32 v148, v8, v8
	v_fmac_f32_e32 v149, v10, v10
	v_fmac_f32_e32 v150, v0, v0
	v_fmac_f32_e32 v151, v2, v2
	v_cvt_pk_bf16_f32 v152, v12, v13
	v_cvt_pk_bf16_f32 v153, v14, v15
	v_cvt_pk_bf16_f32 v154, v4, v5
	v_cvt_pk_bf16_f32 v155, v6, v7
	v_cvt_pk_bf16_f32 v156, v8, v9
	v_cvt_pk_bf16_f32 v157, v10, v11
	v_cvt_pk_bf16_f32 v158, v0, v1
	v_cvt_pk_bf16_f32 v159, v2, v3
	global_store_dwordx4 v[224:225], v[152:155], off
	global_store_dwordx4 v[224:225], v[156:159], off offset:256
	v_add_f32_e32 v144, v144, v145
	v_add_f32_e32 v146, v146, v147
	v_add_f32_e32 v148, v148, v149
	v_add_f32_e32 v150, v150, v151
	v_add_f32_e32 v144, v144, v146
	v_add_f32_e32 v148, v148, v150
	v_add_f32_e32 v144, v144, v148
	v_mov_b32_e32 v145, v144
	s_nop 1
	v_permlane16_swap_b32_e32 v144, v145
	s_nop 0
	v_add_f32_e32 v144, v144, v145
	v_mov_b32_e32 v145, v144
	s_nop 1
	v_permlane32_swap_b32_e32 v144, v145
	s_nop 0
	v_add_f32_e32 v144, v144, v145
	s_and_saveexec_b64 s[50:51], vcc
	global_store_dword v[226:227], v144, off
	s_or_b64 exec, exec, s[50:51]
	s_andn2_b64 vcc, exec, s[4:5]
	s_mov_b64 s[4:5], -1
	s_cbranch_vccnz .LBB0_338
; template <class Epi, class Sched, bool ALIGN_EPI = false, bool SP2 = false, bool FP8 = false>
; __device__ __forceinline__ void gemm_phase(PG8_LAS unsigned char* lds, const Gemm g, const Sched& S, const Epi& E) {
;     ...
; #pragma unroll
;         for (int a = 0; a < 2; ++a)
; #pragma unroll
;             for (int b = 0; b < 2; ++b)
; #pragma unroll
;                 for (int m = 0; m < 4; ++m)
; #pragma unroll
;                     for (int n = 0; n < 2; ++n) { acc[a][b][m][n] = (f32x4){0.f, 0.f, 0.f, 0.f}; if constexpr (FP8) asm volatile("" : "+v"(acc[a][b][m][n])); }
;         cur = nxt; cA = nA; cB = nB; ++ui;
	s_mov_b32 s9, s8
	s_mov_b32 s10, s8
	s_mov_b32 s11, s8
	s_waitcnt lgkmcnt(0)
	v_mov_b64_e32 v[0:1], s[8:9]
	v_mov_b64_e32 v[118:119], s[10:11]
	v_mov_b64_e32 v[114:115], s[10:11]
	v_mov_b64_e32 v[110:111], s[10:11]
	v_mov_b64_e32 v[102:103], s[10:11]
	v_mov_b64_e32 v[94:95], s[10:11]
	v_mov_b64_e32 v[86:87], s[10:11]
	v_mov_b64_e32 v[78:79], s[10:11]
	v_mov_b64_e32 v[70:71], s[10:11]
	v_mov_b64_e32 v[126:127], s[10:11]
	v_mov_b64_e32 v[122:123], s[10:11]
	v_mov_b64_e32 v[106:107], s[10:11]
	v_mov_b64_e32 v[98:99], s[10:11]
	v_mov_b64_e32 v[90:91], s[10:11]
	v_mov_b64_e32 v[82:83], s[10:11]
	v_mov_b64_e32 v[74:75], s[10:11]
	v_mov_b64_e32 v[66:67], s[10:11]
	v_mov_b64_e32 v[54:55], s[10:11]
	v_mov_b64_e32 v[50:51], s[10:11]
	v_mov_b64_e32 v[46:47], s[10:11]
	v_mov_b64_e32 v[38:39], s[10:11]
	v_mov_b64_e32 v[30:31], s[10:11]
	v_mov_b64_e32 v[22:23], s[10:11]
	v_mov_b64_e32 v[14:15], s[10:11]
	v_mov_b64_e32 v[4:5], s[8:9]
	v_mov_b64_e32 v[62:63], s[10:11]
	v_mov_b64_e32 v[58:59], s[10:11]
	v_mov_b64_e32 v[42:43], s[10:11]
	v_mov_b64_e32 v[34:35], s[10:11]
	v_mov_b64_e32 v[26:27], s[10:11]
	v_mov_b64_e32 v[18:19], s[10:11]
	v_mov_b64_e32 v[8:9], s[8:9]
	v_mov_b64_e32 v[2:3], s[10:11]
	v_mov_b64_e32 v[116:117], s[8:9]
	v_mov_b64_e32 v[112:113], s[8:9]
	v_mov_b64_e32 v[108:109], s[8:9]
	v_mov_b64_e32 v[100:101], s[8:9]
	v_mov_b64_e32 v[92:93], s[8:9]
	v_mov_b64_e32 v[84:85], s[8:9]
	v_mov_b64_e32 v[76:77], s[8:9]
	v_mov_b64_e32 v[68:69], s[8:9]
	v_mov_b64_e32 v[124:125], s[8:9]
	v_mov_b64_e32 v[120:121], s[8:9]
	v_mov_b64_e32 v[104:105], s[8:9]
	v_mov_b64_e32 v[96:97], s[8:9]
	v_mov_b64_e32 v[88:89], s[8:9]
	v_mov_b64_e32 v[80:81], s[8:9]
	v_mov_b64_e32 v[72:73], s[8:9]
	v_mov_b64_e32 v[64:65], s[8:9]
	v_mov_b64_e32 v[52:53], s[8:9]
	v_mov_b64_e32 v[48:49], s[8:9]
	v_mov_b64_e32 v[44:45], s[8:9]
	v_mov_b64_e32 v[36:37], s[8:9]
	v_mov_b64_e32 v[28:29], s[8:9]
	v_mov_b64_e32 v[20:21], s[8:9]
	v_mov_b64_e32 v[12:13], s[8:9]
	v_mov_b64_e32 v[6:7], s[10:11]
	v_mov_b64_e32 v[60:61], s[8:9]
	v_mov_b64_e32 v[56:57], s[8:9]
	v_mov_b64_e32 v[40:41], s[8:9]
	v_mov_b64_e32 v[32:33], s[8:9]
	v_mov_b64_e32 v[24:25], s[8:9]
	v_mov_b64_e32 v[16:17], s[8:9]
	v_mov_b64_e32 v[10:11], s[10:11]
	s_andn2_b64 vcc, exec, s[6:7]
	s_cbranch_vccnz .LBB0_337
	s_mov_b32 s100, 1
	s_branch .LBB0_337

;     __device__ __forceinline__ void operator()(const f32x4 (&acc)[2][2][4][2], const Unit& u, int wr, int wc, int fr, int fq) const {
;     ...
;             for (int m = 0; m < 4; ++m) { const size_t r = (size_t)(row0 + ai * HALF + m * 16);
;                 const f32x4 pq = *(const f32x4*)(ssq + r * 16 + 4 * fq);
;                 float ss = (pq[0] + pq[1]) + (pq[2] + pq[3]); ss += __shfl_xor(ss, 16); ss += __shfl_xor(ss, 32);
;                 const float rs = __builtin_amdgcn_rsqf(ss * (1.f / DM) + RMS_EPS);
.LBB0_394:
	s_cmp_eq_u32 s38, s101
	s_cbranch_scc1 .Lmy_rs_cached
	s_mov_b32 s101, s38
	v_lshl_add_u32 v204, s38, 8, v150
	v_ashrrev_i32_e32 v205, 31, v204
	v_lshlrev_b64 v[204:205], 6, v[204:205]
	v_lshl_add_u64 v[204:205], v[136:137], 0, v[204:205]
	s_mov_b64 s[0:1], 0x2000
	global_load_dwordx4 v[170:173], v[204:205], off
	global_load_dwordx4 v[174:177], v[204:205], off offset:1024
	global_load_dwordx4 v[178:181], v[204:205], off offset:2048
	global_load_dwordx4 v[182:185], v[204:205], off offset:3072
	v_lshl_add_u64 v[206:207], v[204:205], 0, s[0:1]
	global_load_dwordx4 v[186:189], v[206:207], off
	global_load_dwordx4 v[190:193], v[206:207], off offset:1024
	global_load_dwordx4 v[194:197], v[206:207], off offset:2048
	global_load_dwordx4 v[198:201], v[206:207], off offset:3072
	v_and_b32_e32 v210, 64, v156
	v_add_u32_e32 v210, 64, v210
	v_xor_b32_e32 v208, 16, v156
	v_cmp_lt_i32_e32 vcc, v208, v210
	s_nop 1
	v_cndmask_b32_e32 v208, v156, v208, vcc
	v_lshlrev_b32_e32 v208, 2, v208
	v_xor_b32_e32 v209, 32, v156
	v_cmp_lt_i32_e32 vcc, v209, v210
	s_nop 1
	v_cndmask_b32_e32 v209, v156, v209, vcc
	v_lshlrev_b32_e32 v209, 2, v209
	s_waitcnt vmcnt(7)
	v_add_f32_e32 v204, v170, v171
	v_add_f32_e32 v205, v172, v173
	v_add_f32_e32 v204, v204, v205
	v_mov_b32_e32 v205, v204
	s_nop 1
	v_permlane16_swap_b32_e32 v204, v205
	s_nop 0
	v_add_f32_e32 v204, v204, v205
	v_mov_b32_e32 v205, v204
	s_nop 1
	v_permlane32_swap_b32_e32 v204, v205
	s_nop 0
	v_add_f32_e32 v204, v204, v205
	v_fmamk_f32 v204, v204, 0x3a800000, v157
	v_rsq_f32_e32 v228, v204
	s_waitcnt vmcnt(6)
	v_add_f32_e32 v204, v174, v175
	v_add_f32_e32 v205, v176, v177
	v_add_f32_e32 v204, v204, v205
	v_mov_b32_e32 v205, v204
	s_nop 1
	v_permlane16_swap_b32_e32 v204, v205
	s_nop 0
	v_add_f32_e32 v204, v204, v205
	v_mov_b32_e32 v205, v204
	s_nop 1
	v_permlane32_swap_b32_e32 v204, v205
	s_nop 0
	v_add_f32_e32 v204, v204, v205
	v_fmamk_f32 v204, v204, 0x3a800000, v157
	v_rsq_f32_e32 v229, v204
	s_waitcnt vmcnt(5)
	v_add_f32_e32 v204, v178, v179
	v_add_f32_e32 v205, v180, v181
	v_add_f32_e32 v204, v204, v205
	v_mov_b32_e32 v205, v204
	s_nop 1
	v_permlane16_swap_b32_e32 v204, v205
	s_nop 0
	v_add_f32_e32 v204, v204, v205
	v_mov_b32_e32 v205, v204
	s_nop 1
	v_permlane32_swap_b32_e32 v204, v205
	s_nop 0
	v_add_f32_e32 v204, v204, v205
	v_fmamk_f32 v204, v204, 0x3a800000, v157
	v_rsq_f32_e32 v230, v204
	s_waitcnt vmcnt(4)
	v_add_f32_e32 v204, v182, v183
	v_add_f32_e32 v205, v184, v185
	v_add_f32_e32 v204, v204, v205
	v_mov_b32_e32 v205, v204
	s_nop 1
	v_permlane16_swap_b32_e32 v204, v205
	s_nop 0
	v_add_f32_e32 v204, v204, v205
	v_mov_b32_e32 v205, v204
	s_nop 1
	v_permlane32_swap_b32_e32 v204, v205
	s_nop 0
	v_add_f32_e32 v204, v204, v205
	v_fmamk_f32 v204, v204, 0x3a800000, v157
	v_rsq_f32_e32 v231, v204
	s_waitcnt vmcnt(3)
	v_add_f32_e32 v204, v186, v187
	v_add_f32_e32 v205, v188, v189
	v_add_f32_e32 v204, v204, v205
	v_mov_b32_e32 v205, v204
	s_nop 1
	v_permlane16_swap_b32_e32 v204, v205
	s_nop 0
	v_add_f32_e32 v204, v204, v205
	v_mov_b32_e32 v205, v204
	s_nop 1
	v_permlane32_swap_b32_e32 v204, v205
	s_nop 0
	v_add_f32_e32 v204, v204, v205
	v_fmamk_f32 v204, v204, 0x3a800000, v157
	v_rsq_f32_e32 v232, v204
	s_waitcnt vmcnt(2)
	v_add_f32_e32 v204, v190, v191
	v_add_f32_e32 v205, v192, v193
	v_add_f32_e32 v204, v204, v205
	v_mov_b32_e32 v205, v204
	s_nop 1
	v_permlane16_swap_b32_e32 v204, v205
	s_nop 0
	v_add_f32_e32 v204, v204, v205
	v_mov_b32_e32 v205, v204
	s_nop 1
	v_permlane32_swap_b32_e32 v204, v205
	s_nop 0
	v_add_f32_e32 v204, v204, v205
	v_fmamk_f32 v204, v204, 0x3a800000, v157
	v_rsq_f32_e32 v233, v204
	s_waitcnt vmcnt(1)
	v_add_f32_e32 v204, v194, v195
	v_add_f32_e32 v205, v196, v197
	v_add_f32_e32 v204, v204, v205
	v_mov_b32_e32 v205, v204
	s_nop 1
	v_permlane16_swap_b32_e32 v204, v205
	s_nop 0
	v_add_f32_e32 v204, v204, v205
	v_mov_b32_e32 v205, v204
	s_nop 1
	v_permlane32_swap_b32_e32 v204, v205
	s_nop 0
	v_add_f32_e32 v204, v204, v205
	v_fmamk_f32 v204, v204, 0x3a800000, v157
	v_rsq_f32_e32 v234, v204
	s_waitcnt vmcnt(0)
	v_add_f32_e32 v204, v198, v199
	v_add_f32_e32 v205, v200, v201
	v_add_f32_e32 v204, v204, v205
	v_mov_b32_e32 v205, v204
	s_nop 1
	v_permlane16_swap_b32_e32 v204, v205
	s_nop 0
	v_add_f32_e32 v204, v204, v205
	v_mov_b32_e32 v205, v204
	s_nop 1
	v_permlane32_swap_b32_e32 v204, v205
	s_nop 0
	v_add_f32_e32 v204, v204, v205
	v_fmamk_f32 v204, v204, 0x3a800000, v157
	v_rsq_f32_e32 v235, v204
	s_nop 0

;     __device__ __forceinline__ void operator()(f32x4 (&acc)[2][2][4][2], const Unit& u, int wr, int wc, int fr, int fq) const {
;     ...
;             for (int m = 0; m < 4; ++m) { const size_t r = (size_t)(row0 + ai * HALF + m * 16); float ss = 0.f;
; #pragma unroll
;                 for (int bj = 0; bj < 2; ++bj) { const u32x4 xw = xv[m][bj];
;                     const f32x4 x0 = {bf_lo(xw.x), bf_hi(xw.x), bf_lo(xw.y), bf_hi(xw.y)}, x1 = {bf_lo(xw.z), bf_hi(xw.z), bf_lo(xw.w), bf_hi(xw.w)};
;                     const f32x4 v0 = acc[ai][bj][m][0] + x0, v1 = acc[ai][bj][m][1] + x1; acc[ai][bj][m][0] = v0; acc[ai][bj][m][1] = v1;
;                     ss += (v0[0] * v0[0] + v0[1] * v0[1]) + (v0[2] * v0[2] + v0[3] * v0[3]) + (v1[0] * v1[0] + v1[1] * v1[1]) + (v1[2] * v1[2] + v1[3] * v1[3]); }
;                 ss += __shfl_xor(ss, 16); ss += __shfl_xor(ss, 32);
;                 if (fq == 0) __hip_atomic_store(ssq + r * 16 + u.pn * 4 + wc, ss, __ATOMIC_RELAXED, __HIP_MEMORY_SCOPE_AGENT); }
.Lmy_ab_p6:
	v_and_b32_e32 v189, 64, v204
	v_xor_b32_e32 v188, 16, v204
	v_add_u32_e32 v207, 64, v189
	v_cmp_lt_i32_e32 vcc, v188, v207
	s_lshl_b32 s40, s6, 2
	s_ashr_i32 s41, s40, 31
	v_cndmask_b32_e32 v188, v204, v188, vcc
	v_lshlrev_b32_e32 v206, 2, v188
	s_waitcnt vmcnt(8)
	v_lshlrev_b32_e32 v188, 16, v180
	v_and_b32_e32 v189, 0xffff0000, v180
	v_lshlrev_b32_e32 v180, 16, v181
	v_and_b32_e32 v181, 0xffff0000, v181
	v_lshlrev_b32_e32 v192, 16, v184
	v_and_b32_e32 v193, 0xffff0000, v184
	v_lshlrev_b32_e32 v184, 16, v185
	v_and_b32_e32 v185, 0xffff0000, v185
	v_lshlrev_b32_e32 v190, 16, v182
	v_and_b32_e32 v191, 0xffff0000, v182
	v_lshlrev_b32_e32 v194, 16, v186
	v_and_b32_e32 v195, 0xffff0000, v186
	v_pk_add_f32 v[126:127], v[126:127], v[180:181]
	v_pk_add_f32 v[124:125], v[124:125], v[188:189]
	v_pk_add_f32 v[118:119], v[118:119], v[184:185]
	v_pk_add_f32 v[116:117], v[116:117], v[192:193]
	v_lshlrev_b32_e32 v182, 16, v183
	v_and_b32_e32 v183, 0xffff0000, v183
	v_lshlrev_b32_e32 v186, 16, v187
	v_and_b32_e32 v187, 0xffff0000, v187
	v_pk_add_f32 v[120:121], v[120:121], v[190:191]
	v_pk_add_f32 v[112:113], v[112:113], v[194:195]
	v_mul_f32_e32 v180, v125, v125
	v_mul_f32_e32 v181, v127, v127
	v_mul_f32_e32 v184, v117, v117
	v_mul_f32_e32 v185, v119, v119
	v_pk_add_f32 v[122:123], v[122:123], v[182:183]
	v_pk_add_f32 v[114:115], v[114:115], v[186:187]
	v_mul_f32_e32 v182, v121, v121
	v_mul_f32_e32 v186, v113, v113
	v_fmac_f32_e32 v180, v124, v124
	v_fmac_f32_e32 v181, v126, v126
	v_fmac_f32_e32 v184, v116, v116
	v_fmac_f32_e32 v185, v118, v118
	v_mul_f32_e32 v183, v123, v123
	v_mul_f32_e32 v187, v115, v115
	v_fmac_f32_e32 v182, v120, v120
	v_fmac_f32_e32 v186, v112, v112
	v_add_f32_e32 v180, v180, v181
	v_add_f32_e32 v181, v184, v185
	v_fmac_f32_e32 v183, v122, v122
	v_fmac_f32_e32 v187, v114, v114
	v_add_f32_e32 v180, v182, v180
	v_add_f32_e32 v181, v186, v181
	v_add_f32_e32 v180, v183, v180
	v_add_f32_e32 v181, v187, v181
	v_add_f32_e32 v180, v180, v181
	v_mov_b32_e32 v181, v180
	s_nop 1
	v_permlane16_swap_b32_e32 v180, v181
	s_nop 0
	v_xor_b32_e32 v182, 32, v204
	v_cmp_lt_i32_e32 vcc, v182, v207
	v_lshlrev_b64 v[188:189], 6, v[176:177]
	s_waitcnt lgkmcnt(0)
	v_add_f32_e32 v180, v180, v181
	v_cndmask_b32_e32 v182, v204, v182, vcc
	v_lshlrev_b32_e32 v207, 2, v182
	v_mov_b32_e32 v181, v180
	s_nop 1
	v_permlane32_swap_b32_e32 v180, v181
	s_nop 0
	s_and_saveexec_b64 s[42:43], s[0:1]
	s_cbranch_execz .LBB0_432
	s_waitcnt lgkmcnt(0)
	v_add_f32_e32 v182, v180, v181
	v_lshl_add_u64 v[180:181], s[10:11], 0, v[188:189]
	v_lshl_add_u64 v[180:181], s[40:41], 2, v[180:181]
	s_lshl_b32 s6, s53, 2
	v_lshl_add_u64 v[180:181], v[180:181], 0, s[6:7]
	global_store_dword v[180:181], v182, off sc1
.LBB0_432:
	s_or_b64 exec, exec, s[42:43]
	v_lshlrev_b32_e32 v180, 16, v148
	s_waitcnt lgkmcnt(0)
	v_and_b32_e32 v181, 0xffff0000, v148
	v_lshlrev_b32_e32 v148, 16, v149
	v_and_b32_e32 v149, 0xffff0000, v149
	v_pk_add_f32 v[110:111], v[110:111], v[148:149]
	v_pk_add_f32 v[108:109], v[108:109], v[180:181]
	v_lshlrev_b32_e32 v182, 16, v150
	v_and_b32_e32 v183, 0xffff0000, v150
	v_mul_f32_e32 v148, v109, v109
	v_mul_f32_e32 v149, v111, v111
	v_pk_add_f32 v[104:105], v[104:105], v[182:183]
	v_fmac_f32_e32 v148, v108, v108
	v_fmac_f32_e32 v149, v110, v110
	v_lshlrev_b32_e32 v150, 16, v151
	v_and_b32_e32 v151, 0xffff0000, v151
	v_add_f32_e32 v148, v148, v149
	v_mul_f32_e32 v149, v105, v105
	v_pk_add_f32 v[106:107], v[106:107], v[150:151]
	v_fmac_f32_e32 v149, v104, v104
	v_add_f32_e32 v148, v149, v148
	v_mul_f32_e32 v149, v107, v107
	v_fmac_f32_e32 v149, v106, v106
	v_add_f32_e32 v182, v149, v148
	v_lshlrev_b32_e32 v148, 16, v144
	v_and_b32_e32 v149, 0xffff0000, v144
	v_lshlrev_b32_e32 v144, 16, v145
	v_and_b32_e32 v145, 0xffff0000, v145
	v_lshlrev_b32_e32 v150, 16, v146
	v_and_b32_e32 v151, 0xffff0000, v146
	v_lshlrev_b32_e32 v180, 16, v147
	v_and_b32_e32 v181, 0xffff0000, v147
	v_pk_add_f32 v[144:145], v[102:103], v[144:145]
	v_pk_add_f32 v[146:147], v[100:101], v[148:149]
	v_pk_add_f32 v[150:151], v[96:97], v[150:151]
	v_mul_f32_e32 v96, v147, v147
	v_mul_f32_e32 v97, v145, v145
	v_fmac_f32_e32 v96, v146, v146
	v_fmac_f32_e32 v97, v144, v144
	v_add_f32_e32 v96, v96, v97
	v_mul_f32_e32 v97, v151, v151
	v_pk_add_f32 v[148:149], v[98:99], v[180:181]
	v_fmac_f32_e32 v97, v150, v150
	v_add_f32_e32 v96, v97, v96
	v_mul_f32_e32 v97, v149, v149
	v_fmac_f32_e32 v97, v148, v148
	v_add_f32_e32 v96, v97, v96
	v_add_f32_e32 v96, v182, v96
	v_mov_b32_e32 v97, v96
	s_nop 1
	v_permlane16_swap_b32_e32 v96, v97
	s_nop 0
	v_lshlrev_b64 v[190:191], 6, v[174:175]
	s_waitcnt lgkmcnt(0)
	v_add_f32_e32 v96, v96, v97
	v_mov_b32_e32 v97, v96
	s_nop 1
	v_permlane32_swap_b32_e32 v96, v97
	s_nop 0
	s_and_saveexec_b64 s[42:43], s[0:1]
	s_cbranch_execz .LBB0_434
	s_waitcnt lgkmcnt(0)
	v_add_f32_e32 v98, v96, v97
	v_lshl_add_u64 v[96:97], s[10:11], 0, v[190:191]
	v_lshl_add_u64 v[96:97], s[40:41], 2, v[96:97]
	s_lshl_b32 s6, s53, 2
	v_lshl_add_u64 v[96:97], v[96:97], 0, s[6:7]
	global_store_dword v[96:97], v98, off sc1
;     __device__ __forceinline__ void operator()(f32x4 (&acc)[2][2][4][2], const Unit& u, int wr, int wc, int fr, int fq) const {
;     ...
;             for (int m = 0; m < 4; ++m) { const size_t r = (size_t)(row0 + ai * HALF + m * 16); float ss = 0.f;
; #pragma unroll
;                 for (int bj = 0; bj < 2; ++bj) { const u32x4 xw = xv[m][bj];
;                     const f32x4 x0 = {bf_lo(xw.x), bf_hi(xw.x), bf_lo(xw.y), bf_hi(xw.y)}, x1 = {bf_lo(xw.z), bf_hi(xw.z), bf_lo(xw.w), bf_hi(xw.w)};
;                     const f32x4 v0 = acc[ai][bj][m][0] + x0, v1 = acc[ai][bj][m][1] + x1; acc[ai][bj][m][0] = v0; acc[ai][bj][m][1] = v1;
;                     ss += (v0[0] * v0[0] + v0[1] * v0[1]) + (v0[2] * v0[2] + v0[3] * v0[3]) + (v1[0] * v1[0] + v1[1] * v1[1]) + (v1[2] * v1[2] + v1[3] * v1[3]); }
;                 ss += __shfl_xor(ss, 16); ss += __shfl_xor(ss, 32);
;                 if (fq == 0) __hip_atomic_store(ssq + r * 16 + u.pn * 4 + wc, ss, __ATOMIC_RELAXED, __HIP_MEMORY_SCOPE_AGENT); }
.LBB0_434:
	s_or_b64 exec, exec, s[42:43]
	v_lshlrev_b32_e32 v96, 16, v140
	s_waitcnt lgkmcnt(0)
	v_and_b32_e32 v97, 0xffff0000, v140
	v_lshlrev_b32_e32 v98, 16, v141
	v_and_b32_e32 v99, 0xffff0000, v141
	v_lshlrev_b32_e32 v100, 16, v142
	v_and_b32_e32 v101, 0xffff0000, v142
	v_lshlrev_b32_e32 v102, 16, v143
	v_and_b32_e32 v103, 0xffff0000, v143
	v_pk_add_f32 v[94:95], v[94:95], v[98:99]
	v_pk_add_f32 v[96:97], v[92:93], v[96:97]
	v_pk_add_f32 v[98:99], v[90:91], v[102:103]
	v_pk_add_f32 v[102:103], v[88:89], v[100:101]
	v_mul_f32_e32 v88, v97, v97
	v_mul_f32_e32 v89, v95, v95
	v_fmac_f32_e32 v88, v96, v96
	v_fmac_f32_e32 v89, v94, v94
	v_add_f32_e32 v88, v88, v89
	v_mul_f32_e32 v89, v103, v103
	v_fmac_f32_e32 v89, v102, v102
	v_add_f32_e32 v88, v89, v88
	v_mul_f32_e32 v89, v99, v99
	v_fmac_f32_e32 v89, v98, v98
	v_add_f32_e32 v182, v89, v88
	v_lshlrev_b32_e32 v88, 16, v136
	v_and_b32_e32 v89, 0xffff0000, v136
	v_lshlrev_b32_e32 v90, 16, v137
	v_and_b32_e32 v91, 0xffff0000, v137
	v_lshlrev_b32_e32 v92, 16, v138
	v_and_b32_e32 v93, 0xffff0000, v138
	v_lshlrev_b32_e32 v100, 16, v139
	v_and_b32_e32 v101, 0xffff0000, v139
	v_pk_add_f32 v[138:139], v[86:87], v[90:91]
	v_pk_add_f32 v[140:141], v[84:85], v[88:89]
	v_pk_add_f32 v[180:181], v[80:81], v[92:93]
	v_mul_f32_e32 v80, v141, v141
	v_mul_f32_e32 v81, v139, v139
	v_fmac_f32_e32 v80, v140, v140
	v_fmac_f32_e32 v81, v138, v138
	v_add_f32_e32 v80, v80, v81
	v_mul_f32_e32 v81, v181, v181
	v_pk_add_f32 v[142:143], v[82:83], v[100:101]
	v_fmac_f32_e32 v81, v180, v180
	v_add_f32_e32 v80, v81, v80
	v_mul_f32_e32 v81, v143, v143
	v_fmac_f32_e32 v81, v142, v142
	v_add_f32_e32 v80, v81, v80
	v_add_f32_e32 v80, v182, v80
	v_mov_b32_e32 v81, v80
	s_nop 1
	v_permlane16_swap_b32_e32 v80, v81
	s_nop 0
	v_lshlrev_b64 v[192:193], 6, v[172:173]
	s_waitcnt lgkmcnt(0)
	v_add_f32_e32 v80, v80, v81
	v_mov_b32_e32 v81, v80
	s_nop 1
	v_permlane32_swap_b32_e32 v80, v81
	s_nop 0
	s_and_saveexec_b64 s[42:43], s[0:1]
	s_cbranch_execz .LBB0_436
	s_waitcnt lgkmcnt(0)
	v_add_f32_e32 v82, v80, v81
	v_lshl_add_u64 v[80:81], s[10:11], 0, v[192:193]
	v_lshl_add_u64 v[80:81], s[40:41], 2, v[80:81]
	s_lshl_b32 s6, s53, 2
	v_lshl_add_u64 v[80:81], v[80:81], 0, s[6:7]
	global_store_dword v[80:81], v82, off sc1
.LBB0_436:
	s_or_b64 exec, exec, s[42:43]
	v_lshlrev_b32_e32 v80, 16, v132
	s_waitcnt lgkmcnt(0)
	v_and_b32_e32 v81, 0xffff0000, v132
	v_lshlrev_b32_e32 v82, 16, v133
	v_and_b32_e32 v83, 0xffff0000, v133
	v_lshlrev_b32_e32 v84, 16, v134
	v_and_b32_e32 v85, 0xffff0000, v134
	v_pk_add_f32 v[100:101], v[78:79], v[82:83]
	v_pk_add_f32 v[132:133], v[76:77], v[80:81]
	v_pk_add_f32 v[136:137], v[72:73], v[84:85]
	v_mul_f32_e32 v72, v133, v133
	v_mul_f32_e32 v73, v101, v101
	v_fmac_f32_e32 v72, v132, v132
	v_fmac_f32_e32 v73, v100, v100
	v_lshlrev_b32_e32 v86, 16, v135
	v_and_b32_e32 v87, 0xffff0000, v135
	v_add_f32_e32 v72, v72, v73
	v_mul_f32_e32 v73, v137, v137
	v_pk_add_f32 v[134:135], v[74:75], v[86:87]
	v_fmac_f32_e32 v73, v136, v136
	v_add_f32_e32 v72, v73, v72
	v_mul_f32_e32 v73, v135, v135
	v_fmac_f32_e32 v73, v134, v134
	v_add_f32_e32 v80, v73, v72
	v_lshlrev_b32_e32 v72, 16, v128
	v_and_b32_e32 v73, 0xffff0000, v128
	v_lshlrev_b32_e32 v74, 16, v129
	v_and_b32_e32 v75, 0xffff0000, v129
	v_lshlrev_b32_e32 v76, 16, v130
	v_and_b32_e32 v77, 0xffff0000, v130
	v_lshlrev_b32_e32 v78, 16, v131
	v_and_b32_e32 v79, 0xffff0000, v131
	v_pk_add_f32 v[128:129], v[70:71], v[74:75]
	v_pk_add_f32 v[130:131], v[68:69], v[72:73]
	v_pk_add_f32 v[184:185], v[64:65], v[76:77]
	v_mul_f32_e32 v64, v131, v131
	v_mul_f32_e32 v65, v129, v129
	v_fmac_f32_e32 v64, v130, v130
	v_fmac_f32_e32 v65, v128, v128
	v_add_f32_e32 v64, v64, v65
	v_mul_f32_e32 v65, v185, v185
	v_pk_add_f32 v[182:183], v[66:67], v[78:79]
	v_fmac_f32_e32 v65, v184, v184
	v_add_f32_e32 v64, v65, v64
	v_mul_f32_e32 v65, v183, v183
	v_fmac_f32_e32 v65, v182, v182
	v_add_f32_e32 v64, v65, v64
	v_add_f32_e32 v64, v80, v64
	v_mov_b32_e32 v65, v64
	s_nop 1
	v_permlane16_swap_b32_e32 v64, v65
	s_nop 0
	v_lshlrev_b64 v[194:195], 6, v[170:171]
	s_waitcnt lgkmcnt(0)
	v_add_f32_e32 v64, v64, v65
	v_mov_b32_e32 v65, v64
	s_nop 1
	v_permlane32_swap_b32_e32 v64, v65
	s_nop 0
	s_and_saveexec_b64 s[42:43], s[0:1]
	s_cbranch_execz .LBB0_438
	s_waitcnt lgkmcnt(0)
	v_add_f32_e32 v66, v64, v65
	v_lshl_add_u64 v[64:65], s[10:11], 0, v[194:195]
	v_lshl_add_u64 v[64:65], s[40:41], 2, v[64:65]
	s_lshl_b32 s6, s53, 2
	v_lshl_add_u64 v[64:65], v[64:65], 0, s[6:7]
	global_store_dword v[64:65], v66, off sc1
;     __device__ __forceinline__ void operator()(f32x4 (&acc)[2][2][4][2], const Unit& u, int wr, int wc, int fr, int fq) const {
;     ...
;                 for (int bj = 0; bj < 2; ++bj) { const size_t off = (size_t)(row0 + ai * HALF + m * 16) * DM + col0 + bj * HALF; xv[m][bj] = *(const u32x4*)(xb + off); }
; #pragma unroll
;             for (int m = 0; m < 4; ++m) { const size_t r = (size_t)(row0 + ai * HALF + m * 16); float ss = 0.f;
; #pragma unroll
;                 for (int bj = 0; bj < 2; ++bj) { const u32x4 xw = xv[m][bj];
;                     const f32x4 x0 = {bf_lo(xw.x), bf_hi(xw.x), bf_lo(xw.y), bf_hi(xw.y)}, x1 = {bf_lo(xw.z), bf_hi(xw.z), bf_lo(xw.w), bf_hi(xw.w)};
;                     const f32x4 v0 = acc[ai][bj][m][0] + x0, v1 = acc[ai][bj][m][1] + x1; acc[ai][bj][m][0] = v0; acc[ai][bj][m][1] = v1;
;                     ss += (v0[0] * v0[0] + v0[1] * v0[1]) + (v0[2] * v0[2] + v0[3] * v0[3]) + (v1[0] * v1[0] + v1[1] * v1[1]) + (v1[2] * v1[2] + v1[3] * v1[3]); }
;                 ss += __shfl_xor(ss, 16); ss += __shfl_xor(ss, 32);
;                 if (fq == 0) __hip_atomic_store(ssq + r * 16 + u.pn * 4 + wc, ss, __ATOMIC_RELAXED, __HIP_MEMORY_SCOPE_AGENT); }
.LBB0_438:
	s_or_b64 exec, exec, s[42:43]
	v_add_u32_e32 v186, 0x80, v176
	v_ashrrev_i32_e32 v187, 31, v186
	s_waitcnt lgkmcnt(0)
	v_lshlrev_b64 v[64:65], 11, v[186:187]
	v_lshl_add_u64 v[64:65], v[196:197], 0, v[64:65]
	s_waitcnt vmcnt(4)
	v_mov_b64_e32 v[208:209], v[222:223]
	v_mov_b64_e32 v[210:211], v[224:225]
	v_mov_b64_e32 v[212:213], v[226:227]
	v_mov_b64_e32 v[214:215], v[228:229]
	v_add_u32_e32 v92, 0x90, v176
	v_add_u32_e32 v90, 0xa0, v176
	v_add_u32_e32 v88, 0xb0, v176
	v_ashrrev_i32_e32 v93, 31, v92
	v_ashrrev_i32_e32 v91, 31, v90
	v_ashrrev_i32_e32 v89, 31, v88
	v_lshlrev_b64 v[64:65], 11, v[92:93]
	v_lshlrev_b64 v[66:67], 11, v[90:91]
	v_lshlrev_b64 v[68:69], 11, v[88:89]
	v_lshl_add_u64 v[64:65], v[196:197], 0, v[64:65]
	v_lshl_add_u64 v[66:67], v[196:197], 0, v[66:67]
	v_lshl_add_u64 v[196:197], v[196:197], 0, v[68:69]
	v_mov_b64_e32 v[84:85], v[230:231]
	v_mov_b64_e32 v[86:87], v[232:233]
	v_mov_b64_e32 v[80:81], v[234:235]
	v_mov_b64_e32 v[82:83], v[236:237]
	v_mov_b64_e32 v[76:77], v[238:239]
	v_mov_b64_e32 v[78:79], v[240:241]
	v_mov_b64_e32 v[72:73], v[242:243]
	v_mov_b64_e32 v[74:75], v[244:245]
	v_mov_b64_e32 v[68:69], v[246:247]
	v_mov_b64_e32 v[70:71], v[248:249]
	s_nop 0
	v_mov_b64_e32 v[64:65], v[250:251]
	v_mov_b64_e32 v[66:67], v[252:253]
	v_lshlrev_b32_e32 v196, 16, v208
	v_and_b32_e32 v197, 0xffff0000, v208
	v_lshlrev_b32_e32 v208, 16, v209
	v_and_b32_e32 v209, 0xffff0000, v209
	v_lshlrev_b32_e32 v218, 16, v212
	v_and_b32_e32 v219, 0xffff0000, v212
	v_lshlrev_b32_e32 v212, 16, v213
	v_and_b32_e32 v213, 0xffff0000, v213
	v_lshlrev_b32_e32 v216, 16, v210
	v_and_b32_e32 v217, 0xffff0000, v210
	v_lshlrev_b32_e32 v210, 16, v211
	v_and_b32_e32 v211, 0xffff0000, v211
	v_lshlrev_b32_e32 v220, 16, v214
	v_and_b32_e32 v221, 0xffff0000, v214
	v_pk_add_f32 v[62:63], v[62:63], v[208:209]
	v_pk_add_f32 v[60:61], v[60:61], v[196:197]
	v_pk_add_f32 v[54:55], v[54:55], v[212:213]
	v_pk_add_f32 v[52:53], v[52:53], v[218:219]
	v_lshlrev_b32_e32 v214, 16, v215
	v_and_b32_e32 v215, 0xffff0000, v215
	v_pk_add_f32 v[58:59], v[58:59], v[210:211]
	v_pk_add_f32 v[56:57], v[56:57], v[216:217]
	v_pk_add_f32 v[48:49], v[48:49], v[220:221]
	v_mul_f32_e32 v196, v61, v61
	v_mul_f32_e32 v197, v63, v63
	v_mul_f32_e32 v210, v53, v53
	v_mul_f32_e32 v211, v55, v55
	v_pk_add_f32 v[50:51], v[50:51], v[214:215]
	v_mul_f32_e32 v208, v57, v57
	v_mul_f32_e32 v212, v49, v49
	v_fmac_f32_e32 v196, v60, v60
	v_fmac_f32_e32 v197, v62, v62
	v_fmac_f32_e32 v210, v52, v52
	v_fmac_f32_e32 v211, v54, v54
	v_mul_f32_e32 v209, v59, v59
	v_mul_f32_e32 v213, v51, v51
	v_fmac_f32_e32 v208, v56, v56
	v_fmac_f32_e32 v212, v48, v48
	v_add_f32_e32 v196, v196, v197
	v_add_f32_e32 v197, v210, v211
	v_fmac_f32_e32 v209, v58, v58
	v_fmac_f32_e32 v213, v50, v50
	v_add_f32_e32 v196, v208, v196
	v_add_f32_e32 v197, v212, v197
	v_add_f32_e32 v196, v209, v196
	v_add_f32_e32 v197, v213, v197
	v_add_f32_e32 v196, v196, v197
	v_mov_b32_e32 v197, v196
	s_nop 1
	v_permlane16_swap_b32_e32 v196, v197
	s_nop 0
	s_waitcnt lgkmcnt(0)
	v_add_f32_e32 v208, v196, v197
	v_mov_b32_e32 v209, v208
	s_nop 1
	v_permlane32_swap_b32_e32 v208, v209
	s_nop 0
	v_lshlrev_b64 v[196:197], 6, v[186:187]
	s_and_saveexec_b64 s[42:43], s[0:1]
	s_cbranch_execz .LBB0_440
	s_waitcnt lgkmcnt(0)
	v_add_f32_e32 v210, v208, v209
	v_lshl_add_u64 v[208:209], s[10:11], 0, v[196:197]
	v_lshl_add_u64 v[208:209], s[40:41], 2, v[208:209]
	s_lshl_b32 s6, s53, 2
	v_lshl_add_u64 v[208:209], v[208:209], 0, s[6:7]
	global_store_dword v[208:209], v210, off sc1
.LBB0_440:
	s_or_b64 exec, exec, s[42:43]
	v_lshlrev_b32_e32 v208, 16, v84
	s_waitcnt lgkmcnt(0)
	v_and_b32_e32 v209, 0xffff0000, v84
	v_lshlrev_b32_e32 v84, 16, v85
	v_and_b32_e32 v85, 0xffff0000, v85
	v_pk_add_f32 v[46:47], v[46:47], v[84:85]
	v_pk_add_f32 v[44:45], v[44:45], v[208:209]
	v_lshlrev_b32_e32 v210, 16, v86
	v_and_b32_e32 v211, 0xffff0000, v86
	v_mul_f32_e32 v84, v45, v45
	v_mul_f32_e32 v85, v47, v47
	v_pk_add_f32 v[40:41], v[40:41], v[210:211]
	v_fmac_f32_e32 v84, v44, v44
	v_fmac_f32_e32 v85, v46, v46
	v_lshlrev_b32_e32 v86, 16, v87
	v_and_b32_e32 v87, 0xffff0000, v87
	v_add_f32_e32 v84, v84, v85
	v_mul_f32_e32 v85, v41, v41
	v_pk_add_f32 v[42:43], v[42:43], v[86:87]
	v_fmac_f32_e32 v85, v40, v40
	v_add_f32_e32 v84, v85, v84
	v_mul_f32_e32 v85, v43, v43
	v_fmac_f32_e32 v85, v42, v42
	v_add_f32_e32 v208, v85, v84
	v_lshlrev_b32_e32 v84, 16, v80
	v_and_b32_e32 v85, 0xffff0000, v80
	v_lshlrev_b32_e32 v80, 16, v81
	v_and_b32_e32 v81, 0xffff0000, v81
	v_lshlrev_b32_e32 v86, 16, v82
	v_and_b32_e32 v87, 0xffff0000, v82
	v_pk_add_f32 v[38:39], v[38:39], v[80:81]
	v_pk_add_f32 v[36:37], v[36:37], v[84:85]
	v_pk_add_f32 v[80:81], v[32:33], v[86:87]
	v_mul_f32_e32 v32, v37, v37
	v_mul_f32_e32 v33, v39, v39
	v_fmac_f32_e32 v32, v36, v36
	v_fmac_f32_e32 v33, v38, v38
	v_lshlrev_b32_e32 v82, 16, v83
	v_and_b32_e32 v83, 0xffff0000, v83
	v_add_f32_e32 v32, v32, v33
	v_mul_f32_e32 v33, v81, v81
	v_pk_add_f32 v[34:35], v[34:35], v[82:83]
	v_fmac_f32_e32 v33, v80, v80
	v_add_f32_e32 v32, v33, v32
	v_mul_f32_e32 v33, v35, v35
	v_fmac_f32_e32 v33, v34, v34
	v_add_f32_e32 v32, v33, v32
	v_add_f32_e32 v32, v208, v32
	v_mov_b32_e32 v33, v32
	s_nop 1
	v_permlane16_swap_b32_e32 v32, v33
	s_nop 0
	v_lshlrev_b64 v[82:83], 6, v[92:93]
	s_waitcnt lgkmcnt(0)
	v_add_f32_e32 v32, v32, v33
	v_mov_b32_e32 v33, v32
	s_nop 1
	v_permlane32_swap_b32_e32 v32, v33
	s_nop 0
	s_and_saveexec_b64 s[42:43], s[0:1]
	s_cbranch_execz .LBB0_442
	s_waitcnt lgkmcnt(0)
	v_add_f32_e32 v84, v32, v33
	v_lshl_add_u64 v[32:33], s[10:11], 0, v[82:83]
	v_lshl_add_u64 v[32:33], s[40:41], 2, v[32:33]
	s_lshl_b32 s6, s53, 2
	v_lshl_add_u64 v[32:33], v[32:33], 0, s[6:7]
	global_store_dword v[32:33], v84, off sc1
;     __device__ __forceinline__ void operator()(f32x4 (&acc)[2][2][4][2], const Unit& u, int wr, int wc, int fr, int fq) const {
;     ...
;             for (int m = 0; m < 4; ++m) { const size_t r = (size_t)(row0 + ai * HALF + m * 16); float ss = 0.f;
; #pragma unroll
;                 for (int bj = 0; bj < 2; ++bj) { const u32x4 xw = xv[m][bj];
;                     const f32x4 x0 = {bf_lo(xw.x), bf_hi(xw.x), bf_lo(xw.y), bf_hi(xw.y)}, x1 = {bf_lo(xw.z), bf_hi(xw.z), bf_lo(xw.w), bf_hi(xw.w)};
;                     const f32x4 v0 = acc[ai][bj][m][0] + x0, v1 = acc[ai][bj][m][1] + x1; acc[ai][bj][m][0] = v0; acc[ai][bj][m][1] = v1;
;                     ss += (v0[0] * v0[0] + v0[1] * v0[1]) + (v0[2] * v0[2] + v0[3] * v0[3]) + (v1[0] * v1[0] + v1[1] * v1[1]) + (v1[2] * v1[2] + v1[3] * v1[3]); }
;                 ss += __shfl_xor(ss, 16); ss += __shfl_xor(ss, 32);
;                 if (fq == 0) __hip_atomic_store(ssq + r * 16 + u.pn * 4 + wc, ss, __ATOMIC_RELAXED, __HIP_MEMORY_SCOPE_AGENT); }
.LBB0_442:
	s_or_b64 exec, exec, s[42:43]
	v_lshlrev_b32_e32 v32, 16, v76
	s_waitcnt lgkmcnt(0)
	v_and_b32_e32 v33, 0xffff0000, v76
	v_lshlrev_b32_e32 v76, 16, v77
	v_and_b32_e32 v77, 0xffff0000, v77
	v_pk_add_f32 v[30:31], v[30:31], v[76:77]
	v_pk_add_f32 v[28:29], v[28:29], v[32:33]
	v_lshlrev_b32_e32 v84, 16, v78
	v_and_b32_e32 v85, 0xffff0000, v78
	v_mul_f32_e32 v32, v29, v29
	v_mul_f32_e32 v33, v31, v31
	v_pk_add_f32 v[24:25], v[24:25], v[84:85]
	v_fmac_f32_e32 v32, v28, v28
	v_fmac_f32_e32 v33, v30, v30
	v_lshlrev_b32_e32 v78, 16, v79
	v_and_b32_e32 v79, 0xffff0000, v79
	v_add_f32_e32 v32, v32, v33
	v_mul_f32_e32 v33, v25, v25
	v_pk_add_f32 v[26:27], v[26:27], v[78:79]
	v_fmac_f32_e32 v33, v24, v24
	v_add_f32_e32 v32, v33, v32
	v_mul_f32_e32 v33, v27, v27
	v_fmac_f32_e32 v33, v26, v26
	v_add_f32_e32 v84, v33, v32
	v_lshlrev_b32_e32 v76, 16, v72
	v_and_b32_e32 v77, 0xffff0000, v72
	v_lshlrev_b32_e32 v32, 16, v73
	v_and_b32_e32 v33, 0xffff0000, v73
	v_lshlrev_b32_e32 v78, 16, v74
	v_and_b32_e32 v79, 0xffff0000, v74
	v_pk_add_f32 v[32:33], v[22:23], v[32:33]
	v_pk_add_f32 v[72:73], v[20:21], v[76:77]
	v_pk_add_f32 v[76:77], v[16:17], v[78:79]
	v_mul_f32_e32 v16, v73, v73
	v_mul_f32_e32 v17, v33, v33
	v_fmac_f32_e32 v16, v72, v72
	v_fmac_f32_e32 v17, v32, v32
	v_lshlrev_b32_e32 v74, 16, v75
	v_and_b32_e32 v75, 0xffff0000, v75
	v_add_f32_e32 v16, v16, v17
	v_mul_f32_e32 v17, v77, v77
	v_pk_add_f32 v[74:75], v[18:19], v[74:75]
	v_fmac_f32_e32 v17, v76, v76
	v_add_f32_e32 v16, v17, v16
	v_mul_f32_e32 v17, v75, v75
	v_fmac_f32_e32 v17, v74, v74
	v_add_f32_e32 v16, v17, v16
	v_add_f32_e32 v16, v84, v16
	v_mov_b32_e32 v17, v16
	s_nop 1
	v_permlane16_swap_b32_e32 v16, v17
	s_nop 0
	v_lshlrev_b64 v[78:79], 6, v[90:91]
	s_waitcnt lgkmcnt(0)
	v_add_f32_e32 v16, v16, v17
	v_mov_b32_e32 v17, v16
	s_nop 1
	v_permlane32_swap_b32_e32 v16, v17
	s_nop 0
	s_and_saveexec_b64 s[42:43], s[0:1]
	s_cbranch_execz .LBB0_444
	s_waitcnt lgkmcnt(0)
	v_add_f32_e32 v18, v16, v17
	v_lshl_add_u64 v[16:17], s[10:11], 0, v[78:79]
	v_lshl_add_u64 v[16:17], s[40:41], 2, v[16:17]
	s_lshl_b32 s6, s53, 2
	v_lshl_add_u64 v[16:17], v[16:17], 0, s[6:7]
	global_store_dword v[16:17], v18, off sc1
.LBB0_444:
	s_or_b64 exec, exec, s[42:43]
	v_lshlrev_b32_e32 v18, 16, v68
	v_and_b32_e32 v19, 0xffff0000, v68
	v_lshlrev_b32_e32 v16, 16, v69
	s_waitcnt lgkmcnt(0)
	v_and_b32_e32 v17, 0xffff0000, v69
	v_lshlrev_b32_e32 v22, 16, v70
	v_and_b32_e32 v23, 0xffff0000, v70
	v_pk_add_f32 v[16:17], v[14:15], v[16:17]
	v_pk_add_f32 v[18:19], v[12:13], v[18:19]
	v_pk_add_f32 v[22:23], v[8:9], v[22:23]
	v_mul_f32_e32 v8, v19, v19
	v_mul_f32_e32 v9, v17, v17
	v_fmac_f32_e32 v8, v18, v18
	v_fmac_f32_e32 v9, v16, v16
	v_lshlrev_b32_e32 v20, 16, v71
	v_and_b32_e32 v21, 0xffff0000, v71
	v_add_f32_e32 v8, v8, v9
	v_mul_f32_e32 v9, v23, v23
	v_pk_add_f32 v[20:21], v[10:11], v[20:21]
	v_fmac_f32_e32 v9, v22, v22
	v_add_f32_e32 v8, v9, v8
	v_mul_f32_e32 v9, v21, v21
	v_fmac_f32_e32 v9, v20, v20
	v_add_f32_e32 v84, v9, v8
	v_lshlrev_b32_e32 v8, 16, v64
	v_and_b32_e32 v9, 0xffff0000, v64
	v_lshlrev_b32_e32 v10, 16, v65
	v_and_b32_e32 v11, 0xffff0000, v65
	v_lshlrev_b32_e32 v12, 16, v66
	v_and_b32_e32 v13, 0xffff0000, v66
	v_lshlrev_b32_e32 v14, 16, v67
	v_and_b32_e32 v15, 0xffff0000, v67
	v_pk_add_f32 v[64:65], v[6:7], v[10:11]
	v_pk_add_f32 v[66:67], v[4:5], v[8:9]
	v_pk_add_f32 v[70:71], v[0:1], v[12:13]
	v_mul_f32_e32 v0, v67, v67
	v_mul_f32_e32 v1, v65, v65
	v_fmac_f32_e32 v0, v66, v66
	v_fmac_f32_e32 v1, v64, v64
	v_add_f32_e32 v0, v0, v1
	v_mul_f32_e32 v1, v71, v71
	v_pk_add_f32 v[68:69], v[2:3], v[14:15]
	v_fmac_f32_e32 v1, v70, v70
	v_add_f32_e32 v0, v1, v0
	v_mul_f32_e32 v1, v69, v69
	v_fmac_f32_e32 v1, v68, v68
	v_add_f32_e32 v0, v1, v0
	v_add_f32_e32 v0, v84, v0
	v_mov_b32_e32 v1, v0
	s_nop 1
	v_permlane16_swap_b32_e32 v0, v1
	s_nop 0
	v_lshlrev_b64 v[84:85], 6, v[88:89]
	s_waitcnt lgkmcnt(0)
	v_add_f32_e32 v0, v0, v1
	v_mov_b32_e32 v1, v0
	s_nop 1
	v_permlane32_swap_b32_e32 v0, v1
	s_nop 0
	s_and_saveexec_b64 s[42:43], s[0:1]
	s_cbranch_execz .LBB0_446
	s_waitcnt lgkmcnt(0)
	v_add_f32_e32 v2, v0, v1
	v_lshl_add_u64 v[0:1], s[10:11], 0, v[84:85]
	v_lshl_add_u64 v[0:1], s[40:41], 2, v[0:1]
	s_lshl_b32 s6, s53, 2
	v_lshl_add_u64 v[0:1], v[0:1], 0, s[6:7]
	global_store_dword v[0:1], v2, off sc1

;     __device__ __forceinline__ void operator()(f32x4 (&acc)[2][2][4][2], const Unit& u, int wr, int wc, int fr, int fq) const {
;     ...
;             for (int n = 0; n < 2; ++n) gv[bj][n] = *(const f32x4*)(gfin + col0 + bj * HALF + 4 * n);
; #pragma unroll
;         for (int ai = 0; ai < 2; ++ai)
; #pragma unroll
;             for (int m = 0; m < 4; ++m) { const size_t r = (size_t)(row0 + ai * HALF + m * 16);
;                 const float* pp = ssq + r * 16 + 4 * fq + dep0;
;                 const float q0 = __hip_atomic_load(pp + 0, __ATOMIC_RELAXED, __HIP_MEMORY_SCOPE_AGENT), q1 = __hip_atomic_load(pp + 1, __ATOMIC_RELAXED, __HIP_MEMORY_SCOPE_AGENT),
;                             q2 = __hip_atomic_load(pp + 2, __ATOMIC_RELAXED, __HIP_MEMORY_SCOPE_AGENT), q3 = __hip_atomic_load(pp + 3, __ATOMIC_RELAXED, __HIP_MEMORY_SCOPE_AGENT);
;                 float tot = (q0 + q1) + (q2 + q3); tot += __shfl_xor(tot, 16); tot += __shfl_xor(tot, 32);
;                 const float rs = __builtin_amdgcn_rsqf(tot * (1.f / DM) + RMS_EPS);
; #pragma unroll
;                 for (int bj = 0; bj < 2; ++bj) { const size_t off = r * DM + col0 + bj * HALF;
;                     *(f32x4*)(out + off) = acc[ai][bj][m][0] * rs * gv[bj][0]; *(f32x4*)(out + off + 4) = acc[ai][bj][m][1] * rs * gv[bj][1]; } }
.LBB0_458:
	s_lshr_b32 s6, s6, 29
	v_lshlrev_b64 v[86:87], 2, v[178:179]
	v_lshl_add_u64 v[178:179], v[160:161], 0, v[188:189]
	s_and_b32 s6, s6, 4
	v_lshl_add_u64 v[8:9], s[18:19], 0, v[86:87]
	v_lshl_add_u64 v[178:179], v[178:179], 0, s[6:7]
	global_load_dwordx4 v[4:7], v[8:9], off offset:16
	global_load_dwordx4 v[12:15], v[8:9], off
	s_waitcnt lgkmcnt(0)
	global_load_dwordx4 v[0:3], v[8:9], off offset:528
	s_nop 0
	global_load_dwordx4 v[8:11], v[8:9], off offset:512
	s_nop 0
	global_load_dwordx4 v[212:215], v[178:179], off sc1
	global_load_dwordx4 v[216:219], v[178:179], off offset:1024 sc1
	global_load_dwordx4 v[220:223], v[178:179], off offset:2048 sc1
	global_load_dwordx4 v[224:227], v[178:179], off offset:3072 sc1
	s_mov_b64 s[60:61], 0x2000
	v_lshl_add_u64 v[244:245], v[178:179], 0, s[60:61]
	global_load_dwordx4 v[228:231], v[244:245], off sc1
	global_load_dwordx4 v[232:235], v[244:245], off offset:1024 sc1
	global_load_dwordx4 v[236:239], v[244:245], off offset:2048 sc1
	global_load_dwordx4 v[240:243], v[244:245], off offset:3072 sc1
	v_lshlrev_b64 v[176:177], 12, v[176:177]
	v_lshl_add_u64 v[176:177], s[20:21], 0, v[176:177]
	v_lshl_add_u64 v[176:177], v[176:177], 0, v[86:87]
	v_lshl_add_u64 v[82:83], v[160:161], 0, v[82:83]
	v_lshl_add_u64 v[82:83], v[82:83], 0, s[6:7]
	s_andn2_b64 vcc, exec, s[4:5]
	s_mov_b64 s[4:5], -1
	s_waitcnt vmcnt(7)
	s_nop 1
	v_mov_b32_e32 v188, v212
	v_mov_b32_e32 v208, v213
	v_mov_b32_e32 v189, v214
	v_mov_b32_e32 v209, v215
	v_pk_add_f32 v[178:179], v[188:189], v[208:209]
	s_nop 0
	v_add_f32_e32 v178, v178, v179
	v_mov_b32_e32 v179, v178
	s_nop 1
	v_permlane16_swap_b32_e32 v178, v179
	s_nop 0
	s_waitcnt lgkmcnt(0)
	v_add_f32_e32 v188, v178, v179
	ds_bpermute_b32 v189, v207, v188
	v_lshl_add_u64 v[178:179], v[160:161], 0, v[190:191]
	v_lshl_add_u64 v[178:179], v[178:179], 0, s[6:7]
	s_waitcnt lgkmcnt(0)
	v_add_f32_e32 v188, v188, v189
	v_fmamk_f32 v188, v188, 0x3a800000, v205
	v_rsq_f32_e32 v188, v188
	s_nop 0
	v_pk_mul_f32 v[124:125], v[124:125], v[188:189] op_sel_hi:[1,0]
	v_pk_mul_f32 v[126:127], v[126:127], v[188:189] op_sel_hi:[1,0]
	v_pk_mul_f32 v[120:121], v[120:121], v[188:189] op_sel_hi:[1,0]
	v_pk_mul_f32 v[122:123], v[122:123], v[188:189] op_sel_hi:[1,0]
	v_pk_mul_f32 v[190:191], v[116:117], v[188:189] op_sel_hi:[1,0]
	v_pk_mul_f32 v[208:209], v[118:119], v[188:189] op_sel_hi:[1,0]
	v_pk_mul_f32 v[210:211], v[112:113], v[188:189] op_sel_hi:[1,0]
	v_pk_mul_f32 v[188:189], v[114:115], v[188:189] op_sel_hi:[1,0]
	v_pk_mul_f32 v[114:115], v[14:15], v[126:127]
	v_pk_mul_f32 v[112:113], v[12:13], v[124:125]
	v_pk_mul_f32 v[118:119], v[6:7], v[122:123]
	v_pk_mul_f32 v[116:117], v[4:5], v[120:121]
	v_pk_mul_f32 v[122:123], v[10:11], v[208:209]
	v_pk_mul_f32 v[120:121], v[8:9], v[190:191]
	v_pk_mul_f32 v[126:127], v[2:3], v[188:189]
	v_pk_mul_f32 v[124:125], v[0:1], v[210:211]
	global_store_dwordx4 v[176:177], v[112:115], off
	global_store_dwordx4 v[176:177], v[116:119], off offset:16
	global_store_dwordx4 v[176:177], v[120:123], off offset:512
	global_store_dwordx4 v[176:177], v[124:127], off offset:528
	s_waitcnt vmcnt(10)
	s_nop 1
	v_mov_b32_e32 v112, v216
	v_mov_b32_e32 v114, v217
	v_mov_b32_e32 v113, v218
	v_mov_b32_e32 v115, v219
	v_pk_add_f32 v[112:113], v[112:113], v[114:115]
	s_nop 0
	v_add_f32_e32 v112, v112, v113
	v_mov_b32_e32 v113, v112
	s_nop 1
	v_permlane16_swap_b32_e32 v112, v113
	s_nop 0
	v_lshl_add_u64 v[114:115], v[160:161], 0, v[192:193]
	v_lshl_add_u64 v[122:123], v[114:115], 0, s[6:7]
	s_waitcnt lgkmcnt(0)
	v_add_f32_e32 v116, v112, v113
	ds_bpermute_b32 v117, v207, v116
	v_lshlrev_b64 v[112:113], 12, v[174:175]
	v_lshl_add_u64 v[112:113], s[20:21], 0, v[112:113]
	v_lshl_add_u64 v[120:121], v[112:113], 0, v[86:87]
	s_waitcnt lgkmcnt(0)
	v_add_f32_e32 v116, v116, v117
	v_fmamk_f32 v116, v116, 0x3a800000, v205
	v_rsq_f32_e32 v116, v116
	s_nop 0
	v_pk_mul_f32 v[108:109], v[108:109], v[116:117] op_sel_hi:[1,0]
	v_pk_mul_f32 v[110:111], v[110:111], v[116:117] op_sel_hi:[1,0]
	v_pk_mul_f32 v[112:113], v[104:105], v[116:117] op_sel_hi:[1,0]
	v_pk_mul_f32 v[114:115], v[106:107], v[116:117] op_sel_hi:[1,0]
	v_pk_mul_f32 v[118:119], v[146:147], v[116:117] op_sel_hi:[1,0]
	v_pk_mul_f32 v[124:125], v[144:145], v[116:117] op_sel_hi:[1,0]
	v_pk_mul_f32 v[126:127], v[150:151], v[116:117] op_sel_hi:[1,0]
	v_pk_mul_f32 v[116:117], v[148:149], v[116:117] op_sel_hi:[1,0]
	v_pk_mul_f32 v[106:107], v[14:15], v[110:111]
	v_pk_mul_f32 v[104:105], v[12:13], v[108:109]
	v_pk_mul_f32 v[110:111], v[6:7], v[114:115]
	v_pk_mul_f32 v[108:109], v[4:5], v[112:113]
	v_pk_mul_f32 v[114:115], v[10:11], v[124:125]
	v_pk_mul_f32 v[112:113], v[8:9], v[118:119]
	v_pk_mul_f32 v[118:119], v[2:3], v[116:117]
	v_pk_mul_f32 v[116:117], v[0:1], v[126:127]
	global_store_dwordx4 v[120:121], v[104:107], off
	global_store_dwordx4 v[120:121], v[108:111], off offset:16
	global_store_dwordx4 v[120:121], v[112:115], off offset:512
	global_store_dwordx4 v[120:121], v[116:119], off offset:528
	s_waitcnt vmcnt(13)
	s_nop 1
	v_mov_b32_e32 v104, v220
	v_mov_b32_e32 v106, v221
	v_mov_b32_e32 v105, v222
	v_mov_b32_e32 v107, v223
	v_pk_add_f32 v[104:105], v[104:105], v[106:107]
	s_nop 0
	v_add_f32_e32 v104, v104, v105
	v_mov_b32_e32 v105, v104
	s_nop 1
	v_permlane16_swap_b32_e32 v104, v105
	s_nop 0
	v_lshl_add_u64 v[106:107], v[160:161], 0, v[194:195]
	v_lshl_add_u64 v[116:117], v[106:107], 0, s[6:7]
	s_waitcnt lgkmcnt(0)
	v_add_f32_e32 v108, v104, v105
	ds_bpermute_b32 v109, v207, v108
	v_lshlrev_b64 v[104:105], 12, v[172:173]
	v_lshl_add_u64 v[104:105], s[20:21], 0, v[104:105]
	v_lshl_add_u64 v[114:115], v[104:105], 0, v[86:87]
	s_waitcnt lgkmcnt(0)
;     __device__ __forceinline__ void operator()(f32x4 (&acc)[2][2][4][2], const Unit& u, int wr, int wc, int fr, int fq) const {
;     ...
;             for (int m = 0; m < 4; ++m) { const size_t r = (size_t)(row0 + ai * HALF + m * 16);
;                 const float* pp = ssq + r * 16 + 4 * fq + dep0;
;                 const float q0 = __hip_atomic_load(pp + 0, __ATOMIC_RELAXED, __HIP_MEMORY_SCOPE_AGENT), q1 = __hip_atomic_load(pp + 1, __ATOMIC_RELAXED, __HIP_MEMORY_SCOPE_AGENT),
;                             q2 = __hip_atomic_load(pp + 2, __ATOMIC_RELAXED, __HIP_MEMORY_SCOPE_AGENT), q3 = __hip_atomic_load(pp + 3, __ATOMIC_RELAXED, __HIP_MEMORY_SCOPE_AGENT);
;                 float tot = (q0 + q1) + (q2 + q3); tot += __shfl_xor(tot, 16); tot += __shfl_xor(tot, 32);
;                 const float rs = __builtin_amdgcn_rsqf(tot * (1.f / DM) + RMS_EPS);
; #pragma unroll
;                 for (int bj = 0; bj < 2; ++bj) { const size_t off = r * DM + col0 + bj * HALF;
;                     *(f32x4*)(out + off) = acc[ai][bj][m][0] * rs * gv[bj][0]; *(f32x4*)(out + off + 4) = acc[ai][bj][m][1] * rs * gv[bj][1]; } }
	v_add_f32_e32 v108, v108, v109
	v_fmamk_f32 v108, v108, 0x3a800000, v205
	v_rsq_f32_e32 v108, v108
	s_nop 0
	v_pk_mul_f32 v[104:105], v[96:97], v[108:109] op_sel_hi:[1,0]
	v_pk_mul_f32 v[94:95], v[94:95], v[108:109] op_sel_hi:[1,0]
	v_pk_mul_f32 v[102:103], v[102:103], v[108:109] op_sel_hi:[1,0]
	v_pk_mul_f32 v[98:99], v[98:99], v[108:109] op_sel_hi:[1,0]
	v_pk_mul_f32 v[106:107], v[140:141], v[108:109] op_sel_hi:[1,0]
	v_pk_mul_f32 v[110:111], v[138:139], v[108:109] op_sel_hi:[1,0]
	v_pk_mul_f32 v[118:119], v[180:181], v[108:109] op_sel_hi:[1,0]
	v_pk_mul_f32 v[112:113], v[142:143], v[108:109] op_sel_hi:[1,0]
	v_pk_mul_f32 v[96:97], v[14:15], v[94:95]
	v_pk_mul_f32 v[94:95], v[12:13], v[104:105]
	v_pk_mul_f32 v[104:105], v[6:7], v[98:99]
	v_pk_mul_f32 v[102:103], v[4:5], v[102:103]
	v_pk_mul_f32 v[108:109], v[10:11], v[110:111]
	v_pk_mul_f32 v[106:107], v[8:9], v[106:107]
	v_pk_mul_f32 v[112:113], v[2:3], v[112:113]
	v_pk_mul_f32 v[110:111], v[0:1], v[118:119]
	global_store_dwordx4 v[114:115], v[94:97], off
	global_store_dwordx4 v[114:115], v[102:105], off offset:16
	global_store_dwordx4 v[114:115], v[106:109], off offset:512
	global_store_dwordx4 v[114:115], v[110:113], off offset:528
	s_waitcnt vmcnt(16)
	s_nop 1
	v_mov_b32_e32 v94, v224
	v_mov_b32_e32 v96, v225
	v_mov_b32_e32 v95, v226
	v_mov_b32_e32 v97, v227
	v_pk_add_f32 v[94:95], v[94:95], v[96:97]
	s_nop 0
	v_add_f32_e32 v94, v94, v95
	v_mov_b32_e32 v95, v94
	s_nop 1
	v_permlane16_swap_b32_e32 v94, v95
	s_nop 0
	v_lshl_add_u64 v[96:97], v[160:161], 0, v[196:197]
	v_lshl_add_u64 v[112:113], v[96:97], 0, s[6:7]
	s_waitcnt lgkmcnt(0)
	v_add_f32_e32 v98, v94, v95
	ds_bpermute_b32 v99, v207, v98
	v_lshlrev_b64 v[94:95], 12, v[170:171]
	v_lshl_add_u64 v[94:95], s[20:21], 0, v[94:95]
	v_lshl_add_u64 v[110:111], v[94:95], 0, v[86:87]
	s_waitcnt lgkmcnt(0)
	v_add_f32_e32 v98, v98, v99
	v_fmamk_f32 v98, v98, 0x3a800000, v205
	v_rsq_f32_e32 v98, v98
	s_nop 0
	v_pk_mul_f32 v[94:95], v[132:133], v[98:99] op_sel_hi:[1,0]
	v_pk_mul_f32 v[96:97], v[100:101], v[98:99] op_sel_hi:[1,0]
	v_pk_mul_f32 v[102:103], v[136:137], v[98:99] op_sel_hi:[1,0]
	v_pk_mul_f32 v[100:101], v[134:135], v[98:99] op_sel_hi:[1,0]
	v_pk_mul_f32 v[106:107], v[130:131], v[98:99] op_sel_hi:[1,0]
	v_pk_mul_f32 v[104:105], v[128:129], v[98:99] op_sel_hi:[1,0]
	v_pk_mul_f32 v[114:115], v[184:185], v[98:99] op_sel_hi:[1,0]
	v_pk_mul_f32 v[108:109], v[182:183], v[98:99] op_sel_hi:[1,0]
	v_pk_mul_f32 v[96:97], v[14:15], v[96:97]
	v_pk_mul_f32 v[94:95], v[12:13], v[94:95]
	v_pk_mul_f32 v[100:101], v[6:7], v[100:101]
	v_pk_mul_f32 v[98:99], v[4:5], v[102:103]
	v_pk_mul_f32 v[104:105], v[10:11], v[104:105]
	v_pk_mul_f32 v[102:103], v[8:9], v[106:107]
	v_pk_mul_f32 v[108:109], v[2:3], v[108:109]
	v_pk_mul_f32 v[106:107], v[0:1], v[114:115]
	global_store_dwordx4 v[110:111], v[94:97], off
	global_store_dwordx4 v[110:111], v[98:101], off offset:16
	global_store_dwordx4 v[110:111], v[102:105], off offset:512
	global_store_dwordx4 v[110:111], v[106:109], off offset:528
	s_waitcnt vmcnt(19)
	s_nop 1
	v_mov_b32_e32 v94, v228
	v_mov_b32_e32 v96, v229
	v_mov_b32_e32 v95, v230
	v_mov_b32_e32 v97, v231
	v_pk_add_f32 v[94:95], v[94:95], v[96:97]
	s_nop 0
	v_add_f32_e32 v94, v94, v95
	v_mov_b32_e32 v95, v94
	s_nop 1
	v_permlane16_swap_b32_e32 v94, v95
	s_nop 0
	s_waitcnt lgkmcnt(0)
	v_add_f32_e32 v96, v94, v95
	ds_bpermute_b32 v97, v207, v96
	v_lshlrev_b64 v[94:95], 12, v[186:187]
	v_lshl_add_u64 v[94:95], s[20:21], 0, v[94:95]
	v_lshl_add_u64 v[94:95], v[94:95], 0, v[86:87]
	s_waitcnt lgkmcnt(0)
	v_add_f32_e32 v96, v96, v97
	v_fmamk_f32 v96, v96, 0x3a800000, v205
	v_rsq_f32_e32 v96, v96
	s_nop 0
	v_pk_mul_f32 v[60:61], v[60:61], v[96:97] op_sel_hi:[1,0]
	v_pk_mul_f32 v[62:63], v[62:63], v[96:97] op_sel_hi:[1,0]
	v_pk_mul_f32 v[56:57], v[56:57], v[96:97] op_sel_hi:[1,0]
	v_pk_mul_f32 v[58:59], v[58:59], v[96:97] op_sel_hi:[1,0]
	v_pk_mul_f32 v[98:99], v[52:53], v[96:97] op_sel_hi:[1,0]
	v_pk_mul_f32 v[100:101], v[54:55], v[96:97] op_sel_hi:[1,0]
	v_pk_mul_f32 v[102:103], v[48:49], v[96:97] op_sel_hi:[1,0]
	v_pk_mul_f32 v[96:97], v[50:51], v[96:97] op_sel_hi:[1,0]
	v_pk_mul_f32 v[50:51], v[14:15], v[62:63]
	v_pk_mul_f32 v[48:49], v[12:13], v[60:61]
	v_pk_mul_f32 v[54:55], v[6:7], v[58:59]
	v_pk_mul_f32 v[52:53], v[4:5], v[56:57]
	v_pk_mul_f32 v[58:59], v[10:11], v[100:101]
	v_pk_mul_f32 v[56:57], v[8:9], v[98:99]
	v_pk_mul_f32 v[62:63], v[2:3], v[96:97]
	v_pk_mul_f32 v[60:61], v[0:1], v[102:103]
	global_store_dwordx4 v[94:95], v[48:51], off
	global_store_dwordx4 v[94:95], v[52:55], off offset:16
	global_store_dwordx4 v[94:95], v[56:59], off offset:512
	global_store_dwordx4 v[94:95], v[60:63], off offset:528
	s_waitcnt vmcnt(22)
	s_nop 1
	v_mov_b32_e32 v48, v232
	v_mov_b32_e32 v50, v233
	v_mov_b32_e32 v49, v234
	v_mov_b32_e32 v51, v235
	v_pk_add_f32 v[48:49], v[48:49], v[50:51]
	s_nop 0
	v_add_f32_e32 v48, v48, v49
	v_mov_b32_e32 v49, v48
	s_nop 1
	v_permlane16_swap_b32_e32 v48, v49
	s_nop 0
	v_lshl_add_u64 v[50:51], v[160:161], 0, v[78:79]
	v_lshl_add_u64 v[50:51], v[50:51], 0, s[6:7]
	s_waitcnt lgkmcnt(0)
;     __device__ __forceinline__ void operator()(f32x4 (&acc)[2][2][4][2], const Unit& u, int wr, int wc, int fr, int fq) const {
;     ...
;             for (int m = 0; m < 4; ++m) { const size_t r = (size_t)(row0 + ai * HALF + m * 16);
;                 const float* pp = ssq + r * 16 + 4 * fq + dep0;
;                 const float q0 = __hip_atomic_load(pp + 0, __ATOMIC_RELAXED, __HIP_MEMORY_SCOPE_AGENT), q1 = __hip_atomic_load(pp + 1, __ATOMIC_RELAXED, __HIP_MEMORY_SCOPE_AGENT),
;                             q2 = __hip_atomic_load(pp + 2, __ATOMIC_RELAXED, __HIP_MEMORY_SCOPE_AGENT), q3 = __hip_atomic_load(pp + 3, __ATOMIC_RELAXED, __HIP_MEMORY_SCOPE_AGENT);
;                 float tot = (q0 + q1) + (q2 + q3); tot += __shfl_xor(tot, 16); tot += __shfl_xor(tot, 32);
;                 const float rs = __builtin_amdgcn_rsqf(tot * (1.f / DM) + RMS_EPS);
; #pragma unroll
;                 for (int bj = 0; bj < 2; ++bj) { const size_t off = r * DM + col0 + bj * HALF;
;                     *(f32x4*)(out + off) = acc[ai][bj][m][0] * rs * gv[bj][0]; *(f32x4*)(out + off + 4) = acc[ai][bj][m][1] * rs * gv[bj][1]; } }
	v_add_f32_e32 v52, v48, v49
	ds_bpermute_b32 v53, v207, v52
	v_lshlrev_b64 v[48:49], 12, v[92:93]
	v_lshl_add_u64 v[48:49], s[20:21], 0, v[48:49]
	v_lshl_add_u64 v[54:55], v[48:49], 0, v[86:87]
	s_waitcnt lgkmcnt(0)
	v_add_f32_e32 v52, v52, v53
	v_fmamk_f32 v52, v52, 0x3a800000, v205
	v_rsq_f32_e32 v52, v52
	s_nop 0
	v_pk_mul_f32 v[44:45], v[44:45], v[52:53] op_sel_hi:[1,0]
	v_pk_mul_f32 v[46:47], v[46:47], v[52:53] op_sel_hi:[1,0]
	v_pk_mul_f32 v[48:49], v[40:41], v[52:53] op_sel_hi:[1,0]
	v_pk_mul_f32 v[40:41], v[42:43], v[52:53] op_sel_hi:[1,0]
	v_pk_mul_f32 v[42:43], v[36:37], v[52:53] op_sel_hi:[1,0]
	v_pk_mul_f32 v[56:57], v[38:39], v[52:53] op_sel_hi:[1,0]
	v_pk_mul_f32 v[58:59], v[80:81], v[52:53] op_sel_hi:[1,0]
	v_pk_mul_f32 v[52:53], v[34:35], v[52:53] op_sel_hi:[1,0]
	v_pk_mul_f32 v[36:37], v[14:15], v[46:47]
	v_pk_mul_f32 v[34:35], v[12:13], v[44:45]
	v_pk_mul_f32 v[40:41], v[6:7], v[40:41]
	v_pk_mul_f32 v[38:39], v[4:5], v[48:49]
	v_pk_mul_f32 v[44:45], v[10:11], v[56:57]
	v_pk_mul_f32 v[42:43], v[8:9], v[42:43]
	v_pk_mul_f32 v[48:49], v[2:3], v[52:53]
	v_pk_mul_f32 v[46:47], v[0:1], v[58:59]
	global_store_dwordx4 v[54:55], v[34:37], off
	global_store_dwordx4 v[54:55], v[38:41], off offset:16
	global_store_dwordx4 v[54:55], v[42:45], off offset:512
	global_store_dwordx4 v[54:55], v[46:49], off offset:528
	s_waitcnt vmcnt(25)
	s_nop 1
	v_mov_b32_e32 v34, v236
	v_mov_b32_e32 v36, v237
	v_mov_b32_e32 v35, v238
	v_mov_b32_e32 v37, v239
	v_pk_add_f32 v[34:35], v[34:35], v[36:37]
	s_nop 0
	v_add_f32_e32 v34, v34, v35
	v_mov_b32_e32 v35, v34
	s_nop 1
	v_permlane16_swap_b32_e32 v34, v35
	s_nop 0
	v_lshl_add_u64 v[36:37], v[160:161], 0, v[84:85]
	v_lshl_add_u64 v[42:43], v[36:37], 0, s[6:7]
	s_waitcnt lgkmcnt(0)
	v_add_f32_e32 v38, v34, v35
	ds_bpermute_b32 v39, v207, v38
	v_lshlrev_b64 v[34:35], 12, v[90:91]
	v_lshl_add_u64 v[34:35], s[20:21], 0, v[34:35]
	v_lshl_add_u64 v[40:41], v[34:35], 0, v[86:87]
	s_waitcnt lgkmcnt(0)
	v_add_f32_e32 v38, v38, v39
	v_fmamk_f32 v38, v38, 0x3a800000, v205
	v_rsq_f32_e32 v38, v38
	s_nop 0
	v_pk_mul_f32 v[28:29], v[28:29], v[38:39] op_sel_hi:[1,0]
	v_pk_mul_f32 v[30:31], v[30:31], v[38:39] op_sel_hi:[1,0]
	v_pk_mul_f32 v[34:35], v[24:25], v[38:39] op_sel_hi:[1,0]
	v_pk_mul_f32 v[36:37], v[26:27], v[38:39] op_sel_hi:[1,0]
	v_pk_mul_f32 v[44:45], v[72:73], v[38:39] op_sel_hi:[1,0]
	v_pk_mul_f32 v[32:33], v[32:33], v[38:39] op_sel_hi:[1,0]
	v_pk_mul_f32 v[46:47], v[76:77], v[38:39] op_sel_hi:[1,0]
	v_pk_mul_f32 v[38:39], v[74:75], v[38:39] op_sel_hi:[1,0]
	v_pk_mul_f32 v[26:27], v[14:15], v[30:31]
	v_pk_mul_f32 v[24:25], v[12:13], v[28:29]
	v_pk_mul_f32 v[30:31], v[6:7], v[36:37]
	v_pk_mul_f32 v[28:29], v[4:5], v[34:35]
	v_pk_mul_f32 v[34:35], v[10:11], v[32:33]
	v_pk_mul_f32 v[32:33], v[8:9], v[44:45]
	v_pk_mul_f32 v[38:39], v[2:3], v[38:39]
	v_pk_mul_f32 v[36:37], v[0:1], v[46:47]
	global_store_dwordx4 v[40:41], v[24:27], off
	global_store_dwordx4 v[40:41], v[28:31], off offset:16
	global_store_dwordx4 v[40:41], v[32:35], off offset:512
	global_store_dwordx4 v[40:41], v[36:39], off offset:528
	s_waitcnt vmcnt(28)
	s_nop 1
	v_mov_b32_e32 v24, v240
	v_mov_b32_e32 v26, v241
	v_mov_b32_e32 v25, v242
	v_mov_b32_e32 v27, v243
	v_pk_add_f32 v[24:25], v[24:25], v[26:27]
	s_nop 0
	v_add_f32_e32 v24, v24, v25
	v_mov_b32_e32 v25, v24
	s_nop 1
	v_permlane16_swap_b32_e32 v24, v25
	s_nop 0
	s_waitcnt lgkmcnt(0)
	v_add_f32_e32 v26, v24, v25
	ds_bpermute_b32 v27, v207, v26
	v_lshlrev_b64 v[24:25], 12, v[88:89]
	v_lshl_add_u64 v[24:25], s[20:21], 0, v[24:25]
	v_lshl_add_u64 v[24:25], v[24:25], 0, v[86:87]
	s_waitcnt lgkmcnt(0)
	v_add_f32_e32 v26, v26, v27
	v_fmamk_f32 v26, v26, 0x3a800000, v205
	v_rsq_f32_e32 v26, v26
	s_nop 0
	v_pk_mul_f32 v[18:19], v[18:19], v[26:27] op_sel_hi:[1,0]
	v_pk_mul_f32 v[16:17], v[16:17], v[26:27] op_sel_hi:[1,0]
	v_pk_mul_f32 v[22:23], v[22:23], v[26:27] op_sel_hi:[1,0]
	v_pk_mul_f32 v[20:21], v[20:21], v[26:27] op_sel_hi:[1,0]
	v_pk_mul_f32 v[28:29], v[66:67], v[26:27] op_sel_hi:[1,0]
	v_pk_mul_f32 v[30:31], v[64:65], v[26:27] op_sel_hi:[1,0]
	v_pk_mul_f32 v[32:33], v[70:71], v[26:27] op_sel_hi:[1,0]
	v_pk_mul_f32 v[26:27], v[68:69], v[26:27] op_sel_hi:[1,0]
	v_pk_mul_f32 v[14:15], v[14:15], v[16:17]
	v_pk_mul_f32 v[12:13], v[12:13], v[18:19]
	v_pk_mul_f32 v[6:7], v[6:7], v[20:21]
	v_pk_mul_f32 v[4:5], v[4:5], v[22:23]
	v_pk_mul_f32 v[10:11], v[10:11], v[30:31]
	v_pk_mul_f32 v[8:9], v[8:9], v[28:29]
	v_pk_mul_f32 v[2:3], v[2:3], v[26:27]
	v_pk_mul_f32 v[0:1], v[0:1], v[32:33]
	global_store_dwordx4 v[24:25], v[12:15], off
	global_store_dwordx4 v[24:25], v[4:7], off offset:16
	global_store_dwordx4 v[24:25], v[8:11], off offset:512
	global_store_dwordx4 v[24:25], v[0:3], off offset:528
	s_cbranch_vccnz .LBB0_423
	s_andn2_b64 vcc, exec, s[8:9]
	s_cbranch_vccnz .LBB0_422
	s_mov_b32 s100, 1
	s_branch .LBB0_422
